# SWA context tiles processed in pairs between ring barriers (2 barriers instead of 4 per item), on top of the SGPR-base DMA addressing
# baseline (speedup 1.0000x reference)
; #define LAS __attribute__((address_space(3)))
; __device__ __forceinline__ void drain_wait() { asm volatile("s_waitcnt vmcnt(0)" ::: "memory"); __syncthreads(); }
; __device__ __forceinline__ void swa_phase(LAS unsigned char* lds, const bf16_t* Q, const bf16_t* K, const bf16_t* V, bf16_t* Ob, const float* sink, float negb) {
;     ...
;         const int item = item_of(it, SW_ITEMS, SW_ITEMS); if (item < 0) break;
;         const int b = item >> 8, kvh = (item >> 6) & 3, tb = item & 63;
;         const size_t ctx0 = (size_t)(MLAT + b * NCTX), lat0 = (size_t)(b * SEQ);
;         const int i_lo = tb == 0 ? 2 : 0, i_hi = tb == 63 ? 4 : 6;
;         const int NT = 4 + (i_hi - i_lo);
;         const DmaLane dl = dma_lane(256, kvh * 64, w, lane);
;     ...
;         dma_tile<1>(lds, K, V, SW_ROW0(0), 256, dl, w);
;         dma_tile<1>(lds + SW_BUF, K, V, SW_ROW0(1), 256, dl, w);
;         dma_tile<1>(lds + 2 * SW_BUF, K, V, SW_ROW0(2), 256, dl, w);
;         const int tq = 128 * tb + 16 * w;
;         const size_t qrow = (size_t)(b * SEQ + tq + l15);
;         bf16x8 qf[4][2];
; #pragma unroll
;         for (int grp = 0; grp < 4; ++grp)
; #pragma unroll
;             for (int ds = 0; ds < 2; ++ds) qf[grp][ds] = *(const bf16x8*)(Q + qrow * DM + (4 * kvh + grp) * 64 + 32 * ds + 8 * g);
;         f32x4 O[4][4]; float ls[4];
; #pragma unroll
;         for (int grp = 0; grp < 4; ++grp) { ls[grp] = 0.f;
; #pragma unroll
;             for (int db = 0; db < 4; ++db) O[grp][db] = (f32x4){0.f, 0.f, 0.f, 0.f}; }
;         drain_wait();
;         for (int t = 0; t < 4; ++t) {
;             dma_tile<1>(lds + ((t + 3) & 3) * SW_BUF, K, V, SW_ROW0(t + 3), 256, dl, w);
;             const LAS unsigned char* buf = lds + (t & 3) * SW_BUF;
;             full_tile<0, 2, 2>(O, ls, qf, negb, buf, buf + 8192, lane, 0);
.LBB0_350:
	s_cmp_lt_i32 s6, 0
	s_cbranch_scc1 .LBB0_357
	s_and_b32 s0, s6, 0x7fffff00
	s_add_i32 s82, s0, 0x8000
	s_lshl_b32 s0, s6, 5
	s_bfe_u32 s42, s6, 0x20006
	s_and_b32 s12, s6, 63
	s_and_b32 s43, s0, 0x7fffe000
	s_cmp_eq_u32 s12, 0
	s_cselect_b32 s7, 2, 0
	s_cmp_eq_u32 s12, 63
	s_cselect_b32 s0, 4, 6
	s_sub_i32 s44, s0, s7
	s_lshl_b64 s[8:9], s[82:83], 9
	s_add_u32 s0, s67, s8
	s_addc_u32 s1, s4, s9
	v_lshl_or_b32 v4, s42, 7, v188
	s_add_u32 s10, s5, s8
	v_or_b32_e32 v212, v4, v189
	s_addc_u32 s11, s58, s9
	s_add_i32 s6, s40, 0x2000
	s_mov_b32 s13, m0
	s_mov_b32 m0, s40
	s_nop 0
	global_load_lds_dwordx4 v212, s[0:1]
	s_mov_b32 m0, s13
	v_or_b32_e32 v213, v4, v190
	s_mov_b32 s0, m0
	s_mov_b32 m0, s6
	s_nop 0
	global_load_lds_dwordx4 v213, s[10:11]
	s_mov_b32 m0, s0
	s_or_b32 s6, s8, 0x8000
	s_add_u32 s0, s67, s6
	s_addc_u32 s1, s4, s9
	s_add_u32 s10, s5, s6
	s_addc_u32 s11, s58, s9
	s_add_i32 s6, s40, 0x4000
	s_mov_b32 s14, m0
	s_mov_b32 m0, s6
	s_nop 0
	global_load_lds_dwordx4 v212, s[0:1]
	s_mov_b32 m0, s14
	s_add_i32 s13, s40, 0x6000
	s_mov_b32 s0, m0
	s_mov_b32 m0, s13
	s_nop 0
	global_load_lds_dwordx4 v213, s[10:11]
	s_mov_b32 m0, s0
	s_or_b32 s6, s8, 0x10000
	s_add_u32 s0, s67, s6
	s_addc_u32 s1, s4, s9
	s_add_u32 s10, s5, s6
	s_addc_u32 s11, s58, s9
	s_add_i32 s6, s40, 0x8000
	s_mov_b32 s14, m0
	s_mov_b32 m0, s6
	s_nop 0
	global_load_lds_dwordx4 v212, s[0:1]
	s_mov_b32 m0, s14
	s_add_i32 s13, s40, 0xa000
	s_mov_b32 s0, m0
	s_mov_b32 m0, s13
	s_nop 0
	global_load_lds_dwordx4 v213, s[10:11]
	s_mov_b32 m0, s0
	s_lshl_b32 s45, s12, 7
	s_add_i32 s0, s45, s39
	s_add_i32 s1, s0, s43
	v_or_b32_e32 v4, s1, v187
	v_ashrrev_i32_e32 v5, 31, v4
	v_lshlrev_b64 v[126:127], 11, v[4:5]
	v_lshl_add_u64 v[4:5], v[122:123], 0, v[126:127]
	s_lshl_b32 s36, s42, 9
	s_mov_b32 s37, s83
	v_lshl_add_u64 v[32:33], v[4:5], 0, s[36:37]
	global_load_dwordx4 v[4:7], v[32:33], off
	global_load_dwordx4 v[8:11], v[32:33], off offset:128
	global_load_dwordx4 v[12:15], v[32:33], off offset:64
	global_load_dwordx4 v[16:19], v[32:33], off offset:192
	global_load_dwordx4 v[20:23], v[32:33], off offset:256
	global_load_dwordx4 v[24:27], v[32:33], off offset:320
	global_load_dwordx4 v[28:31], v[32:33], off offset:384
	s_nop 0
	global_load_dwordx4 v[32:35], v[32:33], off offset:448
	s_lshl_b32 s60, s42, 4
	s_mov_b32 s61, 0
	v_lshl_add_u64 v[214:215], v[120:121], 0, s[60:61]
	global_load_dword v158, v[214:215], off
	global_load_dword v159, v[214:215], off offset:4
	global_load_dword v184, v[214:215], off offset:8
	global_load_dword v185, v[214:215], off offset:12
	s_lshl_b32 s37, s42, 8
	s_add_i32 s46, s44, 4
	s_or_b32 s1, s8, 0x18000
	s_add_u32 s10, s67, s1
	s_addc_u32 s11, s4, s9
	s_add_u32 s8, s5, s1
	s_addc_u32 s9, s58, s9
	s_add_i32 s1, s40, 0xc000
	s_waitcnt vmcnt(0)
	s_barrier
	s_mov_b32 s12, m0
	s_mov_b32 m0, s1
	s_nop 0
	global_load_lds_dwordx4 v212, s[10:11]
	s_mov_b32 m0, s12
	v_add_u32_e32 v91, v154, v192
	s_add_i32 s6, s40, 0xe000
	s_mov_b32 s1, m0
	s_mov_b32 m0, s6
	s_nop 0
	global_load_lds_dwordx4 v213, s[8:9]
	s_mov_b32 m0, s1
	v_mov_b32_e32 v64, 0
	v_mov_b32_e32 v65, 0
	v_mov_b32_e32 v66, 0
	v_mov_b32_e32 v67, 0
	v_mov_b32_e32 v60, 0
	v_mov_b32_e32 v61, 0
	v_mov_b32_e32 v62, 0
	v_mov_b32_e32 v63, 0
	v_mov_b32_e32 v56, 0
	v_mov_b32_e32 v57, 0
	v_mov_b32_e32 v58, 0
	v_mov_b32_e32 v59, 0
	v_mov_b32_e32 v52, 0
	v_mov_b32_e32 v53, 0
	v_mov_b32_e32 v54, 0
	v_mov_b32_e32 v55, 0
	v_mov_b32_e32 v131, 0
	v_mov_b32_e32 v48, 0
	v_mov_b32_e32 v49, 0
	v_mov_b32_e32 v50, 0
	v_mov_b32_e32 v51, 0
	v_mov_b32_e32 v44, 0
	v_mov_b32_e32 v45, 0
	v_mov_b32_e32 v46, 0
	v_mov_b32_e32 v47, 0
	v_mov_b32_e32 v40, 0
	v_mov_b32_e32 v41, 0
	v_mov_b32_e32 v42, 0
	v_mov_b32_e32 v43, 0
	v_mov_b32_e32 v36, 0
	v_mov_b32_e32 v37, 0
	v_mov_b32_e32 v38, 0
	v_mov_b32_e32 v39, 0
	v_mov_b32_e32 v130, 0
	v_mov_b32_e32 v72, 0
	v_mov_b32_e32 v73, 0
	v_mov_b32_e32 v74, 0
	v_mov_b32_e32 v75, 0
	v_mov_b32_e32 v84, 0
	v_mov_b32_e32 v85, 0
	v_mov_b32_e32 v86, 0
	v_mov_b32_e32 v87, 0
	v_mov_b32_e32 v88, 0
	v_mov_b32_e32 v89, 0
	v_mov_b32_e32 v90, 0
	v_mov_b32_e32 v91, 0
	v_mov_b32_e32 v96, 0
	v_mov_b32_e32 v97, 0
	v_mov_b32_e32 v98, 0
	v_mov_b32_e32 v99, 0
	v_mov_b32_e32 v129, 0
	v_mov_b32_e32 v68, 0
	v_mov_b32_e32 v69, 0
	v_mov_b32_e32 v70, 0
	v_mov_b32_e32 v71, 0
	v_mov_b32_e32 v76, 0
	v_mov_b32_e32 v77, 0
	v_mov_b32_e32 v78, 0
	v_mov_b32_e32 v79, 0
	v_mov_b32_e32 v80, 0
	v_mov_b32_e32 v81, 0
	v_mov_b32_e32 v82, 0
	v_mov_b32_e32 v83, 0
	v_mov_b32_e32 v92, 0
	v_mov_b32_e32 v93, 0
	v_mov_b32_e32 v94, 0
	v_mov_b32_e32 v95, 0
	v_mov_b32_e32 v128, 0
	s_lshl_b32 s47, s7, 6
	s_add_i32 s7, s45, s47
	s_addk_i32 s7, 0xff80
	s_ashr_i32 s8, s7, 31
	s_add_u32 s7, s43, s7
	s_addc_u32 s8, 0, s8
	s_mov_b32 s1, 0
	s_mov_b32 s6, 4
	s_mov_b32 s34, 0
	v_add_u32_e32 v100, s34, v191
	v_add3_u32 v135, s34, v203, v198
	v_add_u32_e32 v102, v100, v193
	v_add_u32_e32 v100, v100, v192
	ds_read_b128 v[160:163], v100
	ds_read_b128 v[164:167], v102
	ds_read_b128 v[168:171], v100 offset:2048
	ds_read_b128 v[172:175], v102 offset:2048
	ds_read_b128 v[104:107], v100 offset:4096
	ds_read_b128 v[108:111], v102 offset:4096
	ds_read_b128 v[112:115], v100 offset:6144
	ds_read_b128 v[116:119], v102 offset:6144
	v_add_u32_e32 v103, v135, v199
	v_add_u32_e32 v133, v135, v200
	v_add_u32_e32 v134, v135, v201
	v_add_u32_e32 v135, v135, v202
	s_waitcnt lgkmcnt(4)
; #define LAS __attribute__((address_space(3)))
; __device__ __forceinline__ s16x4 vtr(const LAS unsigned char* p) { return __builtin_bit_cast(s16x4, __builtin_amdgcn_ds_read_tr16_b64_v4i16((LAS v4i16_t*)p)); }
; __device__ __forceinline__ bf16x8 cat8(s16x4 a, s16x4 b) { return (bf16x8){a[0], a[1], a[2], a[3], b[0], b[1], b[2], b[3]}; }
; __device__ __forceinline__ bf16x8 pack8(const f32x4& a, const f32x4& b) { u32x4 w; w.x = pkbf(a[0], a[1]); w.y = pkbf(a[2], a[3]); w.z = pkbf(b[0], b[1]); w.w = pkbf(b[2], b[3]); return __builtin_bit_cast(bf16x8, w); }
;     ...
;     for (int gh = 0; gh < 4 / GPB; ++gh) {
;         f32x4 S[GPB][4];
; #pragma unroll
;         for (int kb = 0; kb < 4; ++kb) {
;             const bf16x8 kf0 = *(const LAS bf16x8*)(kb0 + (16 * kb) * 128 + kx0), kf1 = *(const LAS bf16x8*)(kb0 + (16 * kb) * 128 + kx1);
; #pragma unroll
;             for (int gi = 0; gi < GPB; ++gi) { S[gi][kb] = __builtin_amdgcn_mfma_f32_16x16x32_bf16(kf0, qf[GPB * gh + gi][0], cinit, 0, 0, 0);
;                 S[gi][kb] = __builtin_amdgcn_mfma_f32_16x16x32_bf16(kf1, qf[GPB * gh + gi][1], S[gi][kb], 0, 0, 0); } }
;         bf16x8 pf[GPB][2];
; #pragma unroll
;         for (int gi = 0; gi < GPB; ++gi) {
;             if (MASK) {
; #pragma unroll
;                 for (int kb = 0; kb < 4; ++kb)
; #pragma unroll
;                     for (int i = 0; i < 4; ++i) { const int rel = rel0 + 16 * kb + 4 * g + i; S[gi][kb][i] = ((unsigned)(rel + 128) > 256u) ? NEGBIG : S[gi][kb][i]; }
;             }
;             ls[GPB * gh + gi] += exp_step<4>(S[gi]);
;             pf[gi][0] = pack8(S[gi][0], S[gi][1]); pf[gi][1] = pack8(S[gi][2], S[gi][3]);
;         }
; #pragma unroll
;         for (int kc = 0; kc < 2; ++kc)
; #pragma unroll
;             for (int db = 0; db < 4; ++db) {
;                 const LAS unsigned char* va = vrow + ((db ^ swz) << 5) + (32 * kc) * 128;
;                 const bf16x8 vf = cat8(vtr(va), vtr(va + 16 * 128));
; #pragma unroll
;                 for (int gi = 0; gi < GPB; ++gi) O[GPB * gh + gi][db] = __builtin_amdgcn_mfma_f32_16x16x32_bf16(vf, pf[gi][kc], O[GPB * gh + gi][db], 0, 0, 0);
;             }
;         if (SB == 1) __builtin_amdgcn_sched_barrier(0); else if (SB == 2) __builtin_amdgcn_sched_barrier(0x108);
	v_mfma_f32_16x16x32_bf16 v[136:139], v[160:163], v[4:7], v[0:3]
	v_mfma_f32_16x16x32_bf16 v[140:143], v[168:171], v[4:7], v[0:3]
	v_mfma_f32_16x16x32_bf16 v[136:139], v[164:167], v[12:15], v[136:139]
	v_mfma_f32_16x16x32_bf16 v[140:143], v[172:175], v[12:15], v[140:143]
	ds_read_b64_tr_b16 v[216:217], v103 offset:8192
	ds_read_b64_tr_b16 v[218:219], v103 offset:10240
	ds_read_b64_tr_b16 v[220:221], v133 offset:8192
	ds_read_b64_tr_b16 v[222:223], v133 offset:10240
	ds_read_b64_tr_b16 v[224:225], v134 offset:8192
	ds_read_b64_tr_b16 v[226:227], v134 offset:10240
	ds_read_b64_tr_b16 v[228:229], v135 offset:8192
	ds_read_b64_tr_b16 v[230:231], v135 offset:10240
	v_mfma_f32_16x16x32_bf16 v[176:179], v[160:163], v[8:11], v[0:3]
	v_exp_f32_e32 v136, v136
	v_exp_f32_e32 v137, v137
	v_exp_f32_e32 v138, v138
	v_add_f32_e32 v144, v136, v137
	v_mfma_f32_16x16x32_bf16 v[232:235], v[168:171], v[8:11], v[0:3]
	v_exp_f32_e32 v139, v139
	v_add_f32_e32 v144, v144, v138
	v_exp_f32_e32 v140, v140
	v_add_f32_e32 v144, v144, v139
	v_mfma_f32_16x16x32_bf16 v[176:179], v[164:167], v[16:19], v[176:179]
	v_exp_f32_e32 v141, v141
	v_add_f32_e32 v144, v144, v140
	v_exp_f32_e32 v142, v142
	v_add_f32_e32 v144, v144, v141
	v_cvt_pk_bf16_f32 v136, v136, v137
	v_mfma_f32_16x16x32_bf16 v[232:235], v[172:175], v[16:19], v[232:235]
	v_exp_f32_e32 v143, v143
	v_add_f32_e32 v144, v144, v142
	v_cvt_pk_bf16_f32 v137, v138, v139
	v_cvt_pk_bf16_f32 v138, v140, v141
	v_cvt_pk_bf16_f32 v139, v142, v143
	v_add_f32_e32 v144, v144, v143
	v_add_f32_e32 v131, v131, v144
	s_waitcnt lgkmcnt(0)
	v_mfma_f32_16x16x32_bf16 v[244:247], v[160:163], v[20:23], v[0:3]
	v_exp_f32_e32 v176, v176
	v_exp_f32_e32 v177, v177
	v_mfma_f32_16x16x32_bf16 v[248:251], v[168:171], v[20:23], v[0:3]
	v_exp_f32_e32 v178, v178
	v_add_f32_e32 v144, v176, v177
	v_mfma_f32_16x16x32_bf16 v[244:247], v[164:167], v[24:27], v[244:247]
	v_exp_f32_e32 v179, v179
	v_add_f32_e32 v144, v144, v178
	v_mfma_f32_16x16x32_bf16 v[248:251], v[172:175], v[24:27], v[248:251]
	v_exp_f32_e32 v232, v232
	v_add_f32_e32 v144, v144, v179
	v_mfma_f32_16x16x32_bf16 v[64:67], v[216:219], v[136:139], v[64:67]
	v_exp_f32_e32 v233, v233
	v_add_f32_e32 v144, v144, v232
	v_mfma_f32_16x16x32_bf16 v[60:63], v[220:223], v[136:139], v[60:63]
	v_exp_f32_e32 v234, v234
	v_add_f32_e32 v144, v144, v233
	v_cvt_pk_bf16_f32 v176, v176, v177
	v_mfma_f32_16x16x32_bf16 v[56:59], v[224:227], v[136:139], v[56:59]
	v_exp_f32_e32 v235, v235
	v_add_f32_e32 v144, v144, v234
	v_cvt_pk_bf16_f32 v177, v178, v179
	v_mfma_f32_16x16x32_bf16 v[52:55], v[228:231], v[136:139], v[52:55]
	v_cvt_pk_bf16_f32 v178, v232, v233
	v_cvt_pk_bf16_f32 v179, v234, v235
	v_add_f32_e32 v144, v144, v235
	v_add_f32_e32 v130, v130, v144
	v_mfma_f32_16x16x32_bf16 v[136:139], v[160:163], v[28:31], v[0:3]
	v_exp_f32_e32 v244, v244
	v_exp_f32_e32 v245, v245
	v_mfma_f32_16x16x32_bf16 v[140:143], v[168:171], v[28:31], v[0:3]
	v_exp_f32_e32 v246, v246
	v_add_f32_e32 v144, v244, v245
	v_mfma_f32_16x16x32_bf16 v[136:139], v[164:167], v[32:35], v[136:139]
	v_exp_f32_e32 v247, v247
	v_add_f32_e32 v144, v144, v246
	v_mfma_f32_16x16x32_bf16 v[140:143], v[172:175], v[32:35], v[140:143]
	v_exp_f32_e32 v248, v248
	v_add_f32_e32 v144, v144, v247
	v_mfma_f32_16x16x32_bf16 v[48:51], v[216:219], v[176:179], v[48:51]
	v_exp_f32_e32 v249, v249
	v_add_f32_e32 v144, v144, v248
	v_mfma_f32_16x16x32_bf16 v[44:47], v[220:223], v[176:179], v[44:47]
	v_exp_f32_e32 v250, v250
	v_add_f32_e32 v144, v144, v249
	v_cvt_pk_bf16_f32 v244, v244, v245
	v_mfma_f32_16x16x32_bf16 v[40:43], v[224:227], v[176:179], v[40:43]
	v_exp_f32_e32 v251, v251
	v_add_f32_e32 v144, v144, v250
	v_cvt_pk_bf16_f32 v245, v246, v247
	v_mfma_f32_16x16x32_bf16 v[36:39], v[228:231], v[176:179], v[36:39]
	v_cvt_pk_bf16_f32 v246, v248, v249
	v_cvt_pk_bf16_f32 v247, v250, v251
	v_add_f32_e32 v144, v144, v251
	v_add_f32_e32 v129, v129, v144
	ds_read_b64_tr_b16 v[160:161], v103 offset:12288
	ds_read_b64_tr_b16 v[162:163], v103 offset:14336
	ds_read_b64_tr_b16 v[164:165], v133 offset:12288
	ds_read_b64_tr_b16 v[166:167], v133 offset:14336
	ds_read_b64_tr_b16 v[168:169], v134 offset:12288
	ds_read_b64_tr_b16 v[170:171], v134 offset:14336
	ds_read_b64_tr_b16 v[172:173], v135 offset:12288
	ds_read_b64_tr_b16 v[174:175], v135 offset:14336
	v_mfma_f32_16x16x32_bf16 v[176:179], v[104:107], v[4:7], v[0:3]
	v_exp_f32_e32 v136, v136
	v_exp_f32_e32 v137, v137
	v_mfma_f32_16x16x32_bf16 v[232:235], v[112:115], v[4:7], v[0:3]
	v_exp_f32_e32 v138, v138
	v_add_f32_e32 v144, v136, v137
	v_mfma_f32_16x16x32_bf16 v[176:179], v[108:111], v[12:15], v[176:179]
	v_exp_f32_e32 v139, v139
	v_add_f32_e32 v144, v144, v138
	v_mfma_f32_16x16x32_bf16 v[232:235], v[116:119], v[12:15], v[232:235]
	v_exp_f32_e32 v140, v140
	v_add_f32_e32 v144, v144, v139
	v_mfma_f32_16x16x32_bf16 v[72:75], v[216:219], v[244:247], v[72:75]
	v_exp_f32_e32 v141, v141
	v_add_f32_e32 v144, v144, v140
	v_mfma_f32_16x16x32_bf16 v[84:87], v[220:223], v[244:247], v[84:87]
	v_exp_f32_e32 v142, v142
	v_add_f32_e32 v144, v144, v141
	v_cvt_pk_bf16_f32 v136, v136, v137
	v_mfma_f32_16x16x32_bf16 v[88:91], v[224:227], v[244:247], v[88:91]
	v_exp_f32_e32 v143, v143
	v_add_f32_e32 v144, v144, v142
	v_cvt_pk_bf16_f32 v137, v138, v139
	v_mfma_f32_16x16x32_bf16 v[96:99], v[228:231], v[244:247], v[96:99]
	v_cvt_pk_bf16_f32 v138, v140, v141
	v_cvt_pk_bf16_f32 v139, v142, v143
	v_add_f32_e32 v144, v144, v143
	v_add_f32_e32 v128, v128, v144
	v_mfma_f32_16x16x32_bf16 v[244:247], v[104:107], v[8:11], v[0:3]
	v_exp_f32_e32 v176, v176
	v_exp_f32_e32 v177, v177
	v_mfma_f32_16x16x32_bf16 v[248:251], v[112:115], v[8:11], v[0:3]
	v_exp_f32_e32 v178, v178
	v_add_f32_e32 v144, v176, v177
	v_mfma_f32_16x16x32_bf16 v[244:247], v[108:111], v[16:19], v[244:247]
	v_exp_f32_e32 v179, v179
	v_add_f32_e32 v144, v144, v178
	v_mfma_f32_16x16x32_bf16 v[248:251], v[116:119], v[16:19], v[248:251]
	v_exp_f32_e32 v232, v232
	v_add_f32_e32 v144, v144, v179
	v_mfma_f32_16x16x32_bf16 v[68:71], v[216:219], v[136:139], v[68:71]
	v_exp_f32_e32 v233, v233
	v_add_f32_e32 v144, v144, v232
	v_mfma_f32_16x16x32_bf16 v[76:79], v[220:223], v[136:139], v[76:79]
	v_exp_f32_e32 v234, v234
	v_add_f32_e32 v144, v144, v233
	v_cvt_pk_bf16_f32 v176, v176, v177
	v_mfma_f32_16x16x32_bf16 v[80:83], v[224:227], v[136:139], v[80:83]
	v_exp_f32_e32 v235, v235
	v_add_f32_e32 v144, v144, v234
	v_cvt_pk_bf16_f32 v177, v178, v179
	v_mfma_f32_16x16x32_bf16 v[92:95], v[228:231], v[136:139], v[92:95]
	v_cvt_pk_bf16_f32 v178, v232, v233
	v_cvt_pk_bf16_f32 v179, v234, v235
	v_add_f32_e32 v144, v144, v235
	v_add_f32_e32 v131, v131, v144
	s_waitcnt lgkmcnt(0)
; #define LAS __attribute__((address_space(3)))
; __device__ __forceinline__ s16x4 vtr(const LAS unsigned char* p) { return __builtin_bit_cast(s16x4, __builtin_amdgcn_ds_read_tr16_b64_v4i16((LAS v4i16_t*)p)); }
;     ...
;     for (int gh = 0; gh < 4 / GPB; ++gh) {
;         f32x4 S[GPB][4];
; #pragma unroll
;         for (int kb = 0; kb < 4; ++kb) {
;             const bf16x8 kf0 = *(const LAS bf16x8*)(kb0 + (16 * kb) * 128 + kx0), kf1 = *(const LAS bf16x8*)(kb0 + (16 * kb) * 128 + kx1);
; #pragma unroll
;             for (int gi = 0; gi < GPB; ++gi) { S[gi][kb] = __builtin_amdgcn_mfma_f32_16x16x32_bf16(kf0, qf[GPB * gh + gi][0], cinit, 0, 0, 0);
;                 S[gi][kb] = __builtin_amdgcn_mfma_f32_16x16x32_bf16(kf1, qf[GPB * gh + gi][1], S[gi][kb], 0, 0, 0); } }
;         bf16x8 pf[GPB][2];
; #pragma unroll
;         for (int gi = 0; gi < GPB; ++gi) {
;             if (MASK) {
; #pragma unroll
;                 for (int kb = 0; kb < 4; ++kb)
; #pragma unroll
;                     for (int i = 0; i < 4; ++i) { const int rel = rel0 + 16 * kb + 4 * g + i; S[gi][kb][i] = ((unsigned)(rel + 128) > 256u) ? NEGBIG : S[gi][kb][i]; }
;             }
;             ls[GPB * gh + gi] += exp_step<4>(S[gi]);
;             pf[gi][0] = pack8(S[gi][0], S[gi][1]); pf[gi][1] = pack8(S[gi][2], S[gi][3]);
;         }
; #pragma unroll
;         for (int kc = 0; kc < 2; ++kc)
; #pragma unroll
;             for (int db = 0; db < 4; ++db) {
;                 const LAS unsigned char* va = vrow + ((db ^ swz) << 5) + (32 * kc) * 128;
;                 const bf16x8 vf = cat8(vtr(va), vtr(va + 16 * 128));
; #pragma unroll
;                 for (int gi = 0; gi < GPB; ++gi) O[GPB * gh + gi][db] = __builtin_amdgcn_mfma_f32_16x16x32_bf16(vf, pf[gi][kc], O[GPB * gh + gi][db], 0, 0, 0);
;             }
;         if (SB == 1) __builtin_amdgcn_sched_barrier(0); else if (SB == 2) __builtin_amdgcn_sched_barrier(0x108);
; __device__ __forceinline__ void swa_phase(LAS unsigned char* lds, const bf16_t* Q, const bf16_t* K, const bf16_t* V, bf16_t* Ob, const float* sink, float negb) {
;     ...
;         for (int t = 0; t < 4; ++t) {
;             dma_tile<1>(lds + ((t + 3) & 3) * SW_BUF, K, V, SW_ROW0(t + 3), 256, dl, w);
;             const LAS unsigned char* buf = lds + (t & 3) * SW_BUF;
;             full_tile<0, 2, 2>(O, ls, qf, negb, buf, buf + 8192, lane, 0);
;             ring_wait<2>();
	v_mfma_f32_16x16x32_bf16 v[136:139], v[104:107], v[20:23], v[0:3]
	v_exp_f32_e32 v244, v244
	v_exp_f32_e32 v245, v245
	v_mfma_f32_16x16x32_bf16 v[140:143], v[112:115], v[20:23], v[0:3]
	v_exp_f32_e32 v246, v246
	v_add_f32_e32 v144, v244, v245
	v_mfma_f32_16x16x32_bf16 v[136:139], v[108:111], v[24:27], v[136:139]
	v_exp_f32_e32 v247, v247
	v_add_f32_e32 v144, v144, v246
	v_mfma_f32_16x16x32_bf16 v[140:143], v[116:119], v[24:27], v[140:143]
	v_exp_f32_e32 v248, v248
	v_add_f32_e32 v144, v144, v247
	v_mfma_f32_16x16x32_bf16 v[64:67], v[160:163], v[176:179], v[64:67]
	v_exp_f32_e32 v249, v249
	v_add_f32_e32 v144, v144, v248
	v_mfma_f32_16x16x32_bf16 v[60:63], v[164:167], v[176:179], v[60:63]
	v_exp_f32_e32 v250, v250
	v_add_f32_e32 v144, v144, v249
	v_cvt_pk_bf16_f32 v244, v244, v245
	v_mfma_f32_16x16x32_bf16 v[56:59], v[168:171], v[176:179], v[56:59]
	v_exp_f32_e32 v251, v251
	v_add_f32_e32 v144, v144, v250
	v_cvt_pk_bf16_f32 v245, v246, v247
	v_mfma_f32_16x16x32_bf16 v[52:55], v[172:175], v[176:179], v[52:55]
	v_cvt_pk_bf16_f32 v246, v248, v249
	v_cvt_pk_bf16_f32 v247, v250, v251
	v_add_f32_e32 v144, v144, v251
	v_add_f32_e32 v130, v130, v144
	v_mfma_f32_16x16x32_bf16 v[176:179], v[104:107], v[28:31], v[0:3]
	v_exp_f32_e32 v136, v136
	v_exp_f32_e32 v137, v137
	v_mfma_f32_16x16x32_bf16 v[232:235], v[112:115], v[28:31], v[0:3]
	v_exp_f32_e32 v138, v138
	v_add_f32_e32 v144, v136, v137
	v_mfma_f32_16x16x32_bf16 v[176:179], v[108:111], v[32:35], v[176:179]
	v_exp_f32_e32 v139, v139
	v_add_f32_e32 v144, v144, v138
	v_mfma_f32_16x16x32_bf16 v[232:235], v[116:119], v[32:35], v[232:235]
	v_exp_f32_e32 v140, v140
	v_add_f32_e32 v144, v144, v139
	v_mfma_f32_16x16x32_bf16 v[48:51], v[160:163], v[244:247], v[48:51]
	v_exp_f32_e32 v141, v141
	v_add_f32_e32 v144, v144, v140
	v_mfma_f32_16x16x32_bf16 v[44:47], v[164:167], v[244:247], v[44:47]
	v_exp_f32_e32 v142, v142
	v_add_f32_e32 v144, v144, v141
	v_cvt_pk_bf16_f32 v136, v136, v137
	v_mfma_f32_16x16x32_bf16 v[40:43], v[168:171], v[244:247], v[40:43]
	v_exp_f32_e32 v143, v143
	v_add_f32_e32 v144, v144, v142
	v_cvt_pk_bf16_f32 v137, v138, v139
	v_mfma_f32_16x16x32_bf16 v[36:39], v[172:175], v[244:247], v[36:39]
	v_cvt_pk_bf16_f32 v138, v140, v141
	v_cvt_pk_bf16_f32 v139, v142, v143
	v_add_f32_e32 v144, v144, v143
	v_add_f32_e32 v129, v129, v144
	v_mfma_f32_16x16x32_bf16 v[72:75], v[160:163], v[136:139], v[72:75]
	v_exp_f32_e32 v176, v176
	v_exp_f32_e32 v177, v177
	v_exp_f32_e32 v178, v178
	v_add_f32_e32 v144, v176, v177
	v_mfma_f32_16x16x32_bf16 v[84:87], v[164:167], v[136:139], v[84:87]
	v_exp_f32_e32 v179, v179
	v_add_f32_e32 v144, v144, v178
	v_exp_f32_e32 v232, v232
	v_add_f32_e32 v144, v144, v179
	v_mfma_f32_16x16x32_bf16 v[88:91], v[168:171], v[136:139], v[88:91]
	v_exp_f32_e32 v233, v233
	v_add_f32_e32 v144, v144, v232
	v_exp_f32_e32 v234, v234
	v_add_f32_e32 v144, v144, v233
	v_cvt_pk_bf16_f32 v176, v176, v177
	v_mfma_f32_16x16x32_bf16 v[96:99], v[172:175], v[136:139], v[96:99]
	v_exp_f32_e32 v235, v235
	v_add_f32_e32 v144, v144, v234
	v_cvt_pk_bf16_f32 v177, v178, v179
	v_cvt_pk_bf16_f32 v178, v232, v233
	v_cvt_pk_bf16_f32 v179, v234, v235
	v_add_f32_e32 v144, v144, v235
	v_add_f32_e32 v128, v128, v144
	v_mfma_f32_16x16x32_bf16 v[68:71], v[160:163], v[176:179], v[68:71]
	v_mfma_f32_16x16x32_bf16 v[76:79], v[164:167], v[176:179], v[76:79]
	v_mfma_f32_16x16x32_bf16 v[80:83], v[168:171], v[176:179], v[80:83]
	v_mfma_f32_16x16x32_bf16 v[92:95], v[172:175], v[176:179], v[92:95]
	s_mov_b32 s34, 0x4000
	v_add_u32_e32 v100, s34, v191
	v_add3_u32 v135, s34, v203, v198
	v_add_u32_e32 v102, v100, v193
	v_add_u32_e32 v100, v100, v192
	ds_read_b128 v[160:163], v100
	ds_read_b128 v[164:167], v102
	ds_read_b128 v[168:171], v100 offset:2048
	ds_read_b128 v[172:175], v102 offset:2048
	ds_read_b128 v[104:107], v100 offset:4096
	ds_read_b128 v[108:111], v102 offset:4096
	ds_read_b128 v[112:115], v100 offset:6144
	ds_read_b128 v[116:119], v102 offset:6144
	v_add_u32_e32 v103, v135, v199
	v_add_u32_e32 v133, v135, v200
	v_add_u32_e32 v134, v135, v201
	v_add_u32_e32 v135, v135, v202
	s_waitcnt lgkmcnt(4)
	v_mfma_f32_16x16x32_bf16 v[136:139], v[160:163], v[4:7], v[0:3]
	v_mfma_f32_16x16x32_bf16 v[140:143], v[168:171], v[4:7], v[0:3]
	v_mfma_f32_16x16x32_bf16 v[136:139], v[164:167], v[12:15], v[136:139]
	v_mfma_f32_16x16x32_bf16 v[140:143], v[172:175], v[12:15], v[140:143]
	ds_read_b64_tr_b16 v[216:217], v103 offset:8192
	ds_read_b64_tr_b16 v[218:219], v103 offset:10240
	ds_read_b64_tr_b16 v[220:221], v133 offset:8192
	ds_read_b64_tr_b16 v[222:223], v133 offset:10240
	ds_read_b64_tr_b16 v[224:225], v134 offset:8192
	ds_read_b64_tr_b16 v[226:227], v134 offset:10240
	ds_read_b64_tr_b16 v[228:229], v135 offset:8192
	ds_read_b64_tr_b16 v[230:231], v135 offset:10240
	v_mfma_f32_16x16x32_bf16 v[176:179], v[160:163], v[8:11], v[0:3]
	v_exp_f32_e32 v136, v136
	v_exp_f32_e32 v137, v137
	v_exp_f32_e32 v138, v138
	v_add_f32_e32 v144, v136, v137
	v_mfma_f32_16x16x32_bf16 v[232:235], v[168:171], v[8:11], v[0:3]
	v_exp_f32_e32 v139, v139
	v_add_f32_e32 v144, v144, v138
	v_exp_f32_e32 v140, v140
	v_add_f32_e32 v144, v144, v139
	v_mfma_f32_16x16x32_bf16 v[176:179], v[164:167], v[16:19], v[176:179]
	v_exp_f32_e32 v141, v141
	v_add_f32_e32 v144, v144, v140
	v_exp_f32_e32 v142, v142
	v_add_f32_e32 v144, v144, v141
	v_cvt_pk_bf16_f32 v136, v136, v137
	v_mfma_f32_16x16x32_bf16 v[232:235], v[172:175], v[16:19], v[232:235]
	v_exp_f32_e32 v143, v143
	v_add_f32_e32 v144, v144, v142
	v_cvt_pk_bf16_f32 v137, v138, v139
	v_cvt_pk_bf16_f32 v138, v140, v141
	v_cvt_pk_bf16_f32 v139, v142, v143
	v_add_f32_e32 v144, v144, v143
	v_add_f32_e32 v131, v131, v144
	s_waitcnt lgkmcnt(0)
; #define LAS __attribute__((address_space(3)))
; __device__ __forceinline__ s16x4 vtr(const LAS unsigned char* p) { return __builtin_bit_cast(s16x4, __builtin_amdgcn_ds_read_tr16_b64_v4i16((LAS v4i16_t*)p)); }
; __device__ __forceinline__ bf16x8 cat8(s16x4 a, s16x4 b) { return (bf16x8){a[0], a[1], a[2], a[3], b[0], b[1], b[2], b[3]}; }
; __device__ __forceinline__ bf16x8 pack8(const f32x4& a, const f32x4& b) { u32x4 w; w.x = pkbf(a[0], a[1]); w.y = pkbf(a[2], a[3]); w.z = pkbf(b[0], b[1]); w.w = pkbf(b[2], b[3]); return __builtin_bit_cast(bf16x8, w); }
;     ...
;     for (int gh = 0; gh < 4 / GPB; ++gh) {
;         f32x4 S[GPB][4];
; #pragma unroll
;         for (int kb = 0; kb < 4; ++kb) {
;             const bf16x8 kf0 = *(const LAS bf16x8*)(kb0 + (16 * kb) * 128 + kx0), kf1 = *(const LAS bf16x8*)(kb0 + (16 * kb) * 128 + kx1);
; #pragma unroll
;             for (int gi = 0; gi < GPB; ++gi) { S[gi][kb] = __builtin_amdgcn_mfma_f32_16x16x32_bf16(kf0, qf[GPB * gh + gi][0], cinit, 0, 0, 0);
;                 S[gi][kb] = __builtin_amdgcn_mfma_f32_16x16x32_bf16(kf1, qf[GPB * gh + gi][1], S[gi][kb], 0, 0, 0); } }
;         bf16x8 pf[GPB][2];
; #pragma unroll
;         for (int gi = 0; gi < GPB; ++gi) {
;             if (MASK) {
; #pragma unroll
;                 for (int kb = 0; kb < 4; ++kb)
; #pragma unroll
;                     for (int i = 0; i < 4; ++i) { const int rel = rel0 + 16 * kb + 4 * g + i; S[gi][kb][i] = ((unsigned)(rel + 128) > 256u) ? NEGBIG : S[gi][kb][i]; }
;             }
;             ls[GPB * gh + gi] += exp_step<4>(S[gi]);
;             pf[gi][0] = pack8(S[gi][0], S[gi][1]); pf[gi][1] = pack8(S[gi][2], S[gi][3]);
;         }
; #pragma unroll
;         for (int kc = 0; kc < 2; ++kc)
; #pragma unroll
;             for (int db = 0; db < 4; ++db) {
;                 const LAS unsigned char* va = vrow + ((db ^ swz) << 5) + (32 * kc) * 128;
;                 const bf16x8 vf = cat8(vtr(va), vtr(va + 16 * 128));
; #pragma unroll
;                 for (int gi = 0; gi < GPB; ++gi) O[GPB * gh + gi][db] = __builtin_amdgcn_mfma_f32_16x16x32_bf16(vf, pf[gi][kc], O[GPB * gh + gi][db], 0, 0, 0);
;             }
;         if (SB == 1) __builtin_amdgcn_sched_barrier(0); else if (SB == 2) __builtin_amdgcn_sched_barrier(0x108);
	v_mfma_f32_16x16x32_bf16 v[244:247], v[160:163], v[20:23], v[0:3]
	v_exp_f32_e32 v176, v176
	v_exp_f32_e32 v177, v177
	v_mfma_f32_16x16x32_bf16 v[248:251], v[168:171], v[20:23], v[0:3]
	v_exp_f32_e32 v178, v178
	v_add_f32_e32 v144, v176, v177
	v_mfma_f32_16x16x32_bf16 v[244:247], v[164:167], v[24:27], v[244:247]
	v_exp_f32_e32 v179, v179
	v_add_f32_e32 v144, v144, v178
	v_mfma_f32_16x16x32_bf16 v[248:251], v[172:175], v[24:27], v[248:251]
	v_exp_f32_e32 v232, v232
	v_add_f32_e32 v144, v144, v179
	v_mfma_f32_16x16x32_bf16 v[64:67], v[216:219], v[136:139], v[64:67]
	v_exp_f32_e32 v233, v233
	v_add_f32_e32 v144, v144, v232
	v_mfma_f32_16x16x32_bf16 v[60:63], v[220:223], v[136:139], v[60:63]
	v_exp_f32_e32 v234, v234
	v_add_f32_e32 v144, v144, v233
	v_cvt_pk_bf16_f32 v176, v176, v177
	v_mfma_f32_16x16x32_bf16 v[56:59], v[224:227], v[136:139], v[56:59]
	v_exp_f32_e32 v235, v235
	v_add_f32_e32 v144, v144, v234
	v_cvt_pk_bf16_f32 v177, v178, v179
	v_mfma_f32_16x16x32_bf16 v[52:55], v[228:231], v[136:139], v[52:55]
	v_cvt_pk_bf16_f32 v178, v232, v233
	v_cvt_pk_bf16_f32 v179, v234, v235
	v_add_f32_e32 v144, v144, v235
	v_add_f32_e32 v130, v130, v144
	v_mfma_f32_16x16x32_bf16 v[136:139], v[160:163], v[28:31], v[0:3]
	v_exp_f32_e32 v244, v244
	v_exp_f32_e32 v245, v245
	v_mfma_f32_16x16x32_bf16 v[140:143], v[168:171], v[28:31], v[0:3]
	v_exp_f32_e32 v246, v246
	v_add_f32_e32 v144, v244, v245
	v_mfma_f32_16x16x32_bf16 v[136:139], v[164:167], v[32:35], v[136:139]
	v_exp_f32_e32 v247, v247
	v_add_f32_e32 v144, v144, v246
	v_mfma_f32_16x16x32_bf16 v[140:143], v[172:175], v[32:35], v[140:143]
	v_exp_f32_e32 v248, v248
	v_add_f32_e32 v144, v144, v247
	v_mfma_f32_16x16x32_bf16 v[48:51], v[216:219], v[176:179], v[48:51]
	v_exp_f32_e32 v249, v249
	v_add_f32_e32 v144, v144, v248
	v_mfma_f32_16x16x32_bf16 v[44:47], v[220:223], v[176:179], v[44:47]
	v_exp_f32_e32 v250, v250
	v_add_f32_e32 v144, v144, v249
	v_cvt_pk_bf16_f32 v244, v244, v245
	v_mfma_f32_16x16x32_bf16 v[40:43], v[224:227], v[176:179], v[40:43]
	v_exp_f32_e32 v251, v251
	v_add_f32_e32 v144, v144, v250
	v_cvt_pk_bf16_f32 v245, v246, v247
	v_mfma_f32_16x16x32_bf16 v[36:39], v[228:231], v[176:179], v[36:39]
	v_cvt_pk_bf16_f32 v246, v248, v249
	v_cvt_pk_bf16_f32 v247, v250, v251
	v_add_f32_e32 v144, v144, v251
	v_add_f32_e32 v129, v129, v144
	ds_read_b64_tr_b16 v[160:161], v103 offset:12288
	ds_read_b64_tr_b16 v[162:163], v103 offset:14336
	ds_read_b64_tr_b16 v[164:165], v133 offset:12288
	ds_read_b64_tr_b16 v[166:167], v133 offset:14336
	ds_read_b64_tr_b16 v[168:169], v134 offset:12288
	ds_read_b64_tr_b16 v[170:171], v134 offset:14336
	ds_read_b64_tr_b16 v[172:173], v135 offset:12288
	ds_read_b64_tr_b16 v[174:175], v135 offset:14336
	v_mfma_f32_16x16x32_bf16 v[176:179], v[104:107], v[4:7], v[0:3]
	v_exp_f32_e32 v136, v136
	v_exp_f32_e32 v137, v137
	v_mfma_f32_16x16x32_bf16 v[232:235], v[112:115], v[4:7], v[0:3]
	v_exp_f32_e32 v138, v138
	v_add_f32_e32 v144, v136, v137
	v_mfma_f32_16x16x32_bf16 v[176:179], v[108:111], v[12:15], v[176:179]
	v_exp_f32_e32 v139, v139
	v_add_f32_e32 v144, v144, v138
	v_mfma_f32_16x16x32_bf16 v[232:235], v[116:119], v[12:15], v[232:235]
	v_exp_f32_e32 v140, v140
	v_add_f32_e32 v144, v144, v139
	v_mfma_f32_16x16x32_bf16 v[72:75], v[216:219], v[244:247], v[72:75]
	v_exp_f32_e32 v141, v141
	v_add_f32_e32 v144, v144, v140
	v_mfma_f32_16x16x32_bf16 v[84:87], v[220:223], v[244:247], v[84:87]
	v_exp_f32_e32 v142, v142
	v_add_f32_e32 v144, v144, v141
	v_cvt_pk_bf16_f32 v136, v136, v137
	v_mfma_f32_16x16x32_bf16 v[88:91], v[224:227], v[244:247], v[88:91]
	v_exp_f32_e32 v143, v143
	v_add_f32_e32 v144, v144, v142
	v_cvt_pk_bf16_f32 v137, v138, v139
	v_mfma_f32_16x16x32_bf16 v[96:99], v[228:231], v[244:247], v[96:99]
	v_cvt_pk_bf16_f32 v138, v140, v141
	v_cvt_pk_bf16_f32 v139, v142, v143
	v_add_f32_e32 v144, v144, v143
	v_add_f32_e32 v128, v128, v144
	v_mfma_f32_16x16x32_bf16 v[244:247], v[104:107], v[8:11], v[0:3]
	v_exp_f32_e32 v176, v176
	v_exp_f32_e32 v177, v177
	v_mfma_f32_16x16x32_bf16 v[248:251], v[112:115], v[8:11], v[0:3]
	v_exp_f32_e32 v178, v178
	v_add_f32_e32 v144, v176, v177
	v_mfma_f32_16x16x32_bf16 v[244:247], v[108:111], v[16:19], v[244:247]
	v_exp_f32_e32 v179, v179
	v_add_f32_e32 v144, v144, v178
	v_mfma_f32_16x16x32_bf16 v[248:251], v[116:119], v[16:19], v[248:251]
	v_exp_f32_e32 v232, v232
	v_add_f32_e32 v144, v144, v179
	v_mfma_f32_16x16x32_bf16 v[68:71], v[216:219], v[136:139], v[68:71]
	v_exp_f32_e32 v233, v233
	v_add_f32_e32 v144, v144, v232
	v_mfma_f32_16x16x32_bf16 v[76:79], v[220:223], v[136:139], v[76:79]
	v_exp_f32_e32 v234, v234
	v_add_f32_e32 v144, v144, v233
	v_cvt_pk_bf16_f32 v176, v176, v177
	v_mfma_f32_16x16x32_bf16 v[80:83], v[224:227], v[136:139], v[80:83]
	v_exp_f32_e32 v235, v235
	v_add_f32_e32 v144, v144, v234
	v_cvt_pk_bf16_f32 v177, v178, v179
	v_mfma_f32_16x16x32_bf16 v[92:95], v[228:231], v[136:139], v[92:95]
	v_cvt_pk_bf16_f32 v178, v232, v233
	v_cvt_pk_bf16_f32 v179, v234, v235
	v_add_f32_e32 v144, v144, v235
	v_add_f32_e32 v131, v131, v144
	s_waitcnt lgkmcnt(0)
; #define LAS __attribute__((address_space(3)))
; __device__ __forceinline__ s16x4 vtr(const LAS unsigned char* p) { return __builtin_bit_cast(s16x4, __builtin_amdgcn_ds_read_tr16_b64_v4i16((LAS v4i16_t*)p)); }
;     ...
;     for (int gh = 0; gh < 4 / GPB; ++gh) {
;         f32x4 S[GPB][4];
; #pragma unroll
;         for (int kb = 0; kb < 4; ++kb) {
;             const bf16x8 kf0 = *(const LAS bf16x8*)(kb0 + (16 * kb) * 128 + kx0), kf1 = *(const LAS bf16x8*)(kb0 + (16 * kb) * 128 + kx1);
; #pragma unroll
;             for (int gi = 0; gi < GPB; ++gi) { S[gi][kb] = __builtin_amdgcn_mfma_f32_16x16x32_bf16(kf0, qf[GPB * gh + gi][0], cinit, 0, 0, 0);
;                 S[gi][kb] = __builtin_amdgcn_mfma_f32_16x16x32_bf16(kf1, qf[GPB * gh + gi][1], S[gi][kb], 0, 0, 0); } }
;         bf16x8 pf[GPB][2];
; #pragma unroll
;         for (int gi = 0; gi < GPB; ++gi) {
;             if (MASK) {
; #pragma unroll
;                 for (int kb = 0; kb < 4; ++kb)
; #pragma unroll
;                     for (int i = 0; i < 4; ++i) { const int rel = rel0 + 16 * kb + 4 * g + i; S[gi][kb][i] = ((unsigned)(rel + 128) > 256u) ? NEGBIG : S[gi][kb][i]; }
;             }
;             ls[GPB * gh + gi] += exp_step<4>(S[gi]);
;             pf[gi][0] = pack8(S[gi][0], S[gi][1]); pf[gi][1] = pack8(S[gi][2], S[gi][3]);
;         }
; #pragma unroll
;         for (int kc = 0; kc < 2; ++kc)
; #pragma unroll
;             for (int db = 0; db < 4; ++db) {
;                 const LAS unsigned char* va = vrow + ((db ^ swz) << 5) + (32 * kc) * 128;
;                 const bf16x8 vf = cat8(vtr(va), vtr(va + 16 * 128));
; #pragma unroll
;                 for (int gi = 0; gi < GPB; ++gi) O[GPB * gh + gi][db] = __builtin_amdgcn_mfma_f32_16x16x32_bf16(vf, pf[gi][kc], O[GPB * gh + gi][db], 0, 0, 0);
;             }
;         if (SB == 1) __builtin_amdgcn_sched_barrier(0); else if (SB == 2) __builtin_amdgcn_sched_barrier(0x108);
; __device__ __forceinline__ void swa_phase(LAS unsigned char* lds, const bf16_t* Q, const bf16_t* K, const bf16_t* V, bf16_t* Ob, const float* sink, float negb) {
;     ...
;         for (int t = 0; t < 4; ++t) {
;             dma_tile<1>(lds + ((t + 3) & 3) * SW_BUF, K, V, SW_ROW0(t + 3), 256, dl, w);
;             const LAS unsigned char* buf = lds + (t & 3) * SW_BUF;
;             full_tile<0, 2, 2>(O, ls, qf, negb, buf, buf + 8192, lane, 0);
;             ring_wait<2>();
	v_mfma_f32_16x16x32_bf16 v[136:139], v[104:107], v[20:23], v[0:3]
	v_exp_f32_e32 v244, v244
	v_exp_f32_e32 v245, v245
	v_mfma_f32_16x16x32_bf16 v[140:143], v[112:115], v[20:23], v[0:3]
	v_exp_f32_e32 v246, v246
	v_add_f32_e32 v144, v244, v245
	v_mfma_f32_16x16x32_bf16 v[136:139], v[108:111], v[24:27], v[136:139]
	v_exp_f32_e32 v247, v247
	v_add_f32_e32 v144, v144, v246
	v_mfma_f32_16x16x32_bf16 v[140:143], v[116:119], v[24:27], v[140:143]
	v_exp_f32_e32 v248, v248
	v_add_f32_e32 v144, v144, v247
	v_mfma_f32_16x16x32_bf16 v[64:67], v[160:163], v[176:179], v[64:67]
	v_exp_f32_e32 v249, v249
	v_add_f32_e32 v144, v144, v248
	v_mfma_f32_16x16x32_bf16 v[60:63], v[164:167], v[176:179], v[60:63]
	v_exp_f32_e32 v250, v250
	v_add_f32_e32 v144, v144, v249
	v_cvt_pk_bf16_f32 v244, v244, v245
	v_mfma_f32_16x16x32_bf16 v[56:59], v[168:171], v[176:179], v[56:59]
	v_exp_f32_e32 v251, v251
	v_add_f32_e32 v144, v144, v250
	v_cvt_pk_bf16_f32 v245, v246, v247
	v_mfma_f32_16x16x32_bf16 v[52:55], v[172:175], v[176:179], v[52:55]
	v_cvt_pk_bf16_f32 v246, v248, v249
	v_cvt_pk_bf16_f32 v247, v250, v251
	v_add_f32_e32 v144, v144, v251
	v_add_f32_e32 v130, v130, v144
	v_mfma_f32_16x16x32_bf16 v[176:179], v[104:107], v[28:31], v[0:3]
	v_exp_f32_e32 v136, v136
	v_exp_f32_e32 v137, v137
	v_mfma_f32_16x16x32_bf16 v[232:235], v[112:115], v[28:31], v[0:3]
	v_exp_f32_e32 v138, v138
	v_add_f32_e32 v144, v136, v137
	v_mfma_f32_16x16x32_bf16 v[176:179], v[108:111], v[32:35], v[176:179]
	v_exp_f32_e32 v139, v139
	v_add_f32_e32 v144, v144, v138
	v_mfma_f32_16x16x32_bf16 v[232:235], v[116:119], v[32:35], v[232:235]
	v_exp_f32_e32 v140, v140
	v_add_f32_e32 v144, v144, v139
	v_mfma_f32_16x16x32_bf16 v[48:51], v[160:163], v[244:247], v[48:51]
	v_exp_f32_e32 v141, v141
	v_add_f32_e32 v144, v144, v140
	v_mfma_f32_16x16x32_bf16 v[44:47], v[164:167], v[244:247], v[44:47]
	v_exp_f32_e32 v142, v142
	v_add_f32_e32 v144, v144, v141
	v_cvt_pk_bf16_f32 v136, v136, v137
	v_mfma_f32_16x16x32_bf16 v[40:43], v[168:171], v[244:247], v[40:43]
	v_exp_f32_e32 v143, v143
	v_add_f32_e32 v144, v144, v142
	v_cvt_pk_bf16_f32 v137, v138, v139
	v_mfma_f32_16x16x32_bf16 v[36:39], v[172:175], v[244:247], v[36:39]
	v_cvt_pk_bf16_f32 v138, v140, v141
	v_cvt_pk_bf16_f32 v139, v142, v143
	v_add_f32_e32 v144, v144, v143
	v_add_f32_e32 v129, v129, v144
	v_mfma_f32_16x16x32_bf16 v[72:75], v[160:163], v[136:139], v[72:75]
	v_exp_f32_e32 v176, v176
	v_exp_f32_e32 v177, v177
	v_exp_f32_e32 v178, v178
	v_add_f32_e32 v144, v176, v177
	v_mfma_f32_16x16x32_bf16 v[84:87], v[164:167], v[136:139], v[84:87]
	v_exp_f32_e32 v179, v179
	v_add_f32_e32 v144, v144, v178
	v_exp_f32_e32 v232, v232
	v_add_f32_e32 v144, v144, v179
	v_mfma_f32_16x16x32_bf16 v[88:91], v[168:171], v[136:139], v[88:91]
	v_exp_f32_e32 v233, v233
	v_add_f32_e32 v144, v144, v232
	v_exp_f32_e32 v234, v234
	v_add_f32_e32 v144, v144, v233
	v_cvt_pk_bf16_f32 v176, v176, v177
	v_mfma_f32_16x16x32_bf16 v[96:99], v[172:175], v[136:139], v[96:99]
	v_exp_f32_e32 v235, v235
	v_add_f32_e32 v144, v144, v234
	v_cvt_pk_bf16_f32 v177, v178, v179
	v_cvt_pk_bf16_f32 v178, v232, v233
	v_cvt_pk_bf16_f32 v179, v234, v235
	v_add_f32_e32 v144, v144, v235
	v_add_f32_e32 v128, v128, v144
	v_mfma_f32_16x16x32_bf16 v[68:71], v[160:163], v[176:179], v[68:71]
	v_mfma_f32_16x16x32_bf16 v[76:79], v[164:167], v[176:179], v[76:79]
	v_mfma_f32_16x16x32_bf16 v[80:83], v[168:171], v[176:179], v[80:83]
	v_mfma_f32_16x16x32_bf16 v[92:95], v[172:175], v[176:179], v[92:95]
	s_waitcnt vmcnt(0)
	s_barrier
	s_cmp_lt_u32 s6, s46
	s_cselect_b32 s11, s8, 0
	s_cselect_b32 s10, s7, s82
	s_lshl_b64 s[10:11], s[10:11], 9
	s_add_u32 s12, s67, s10
	s_addc_u32 s13, s4, s11
	s_add_u32 s10, s5, s10
	s_addc_u32 s11, s58, s11
	s_add_i32 s9, s40, s1
	s_mov_b32 s15, m0
	s_mov_b32 m0, s9
	s_nop 0
	global_load_lds_dwordx4 v212, s[12:13]
	s_mov_b32 m0, s15
	s_add_i32 s14, s9, 0x2000
	s_mov_b32 s9, m0
	s_mov_b32 m0, s14
	s_nop 0
	global_load_lds_dwordx4 v213, s[10:11]
	s_mov_b32 m0, s9
	s_addk_i32 s1, 0x4000
	s_add_u32 s7, s7, 64
	s_addc_u32 s8, s8, 0
	s_add_i32 s6, s6, 1
	s_cmp_lt_u32 s6, s46
	s_cselect_b32 s11, s8, 0
	s_cselect_b32 s10, s7, s82
	s_lshl_b64 s[10:11], s[10:11], 9
	s_add_u32 s12, s67, s10
	s_addc_u32 s13, s4, s11
	s_add_u32 s10, s5, s10
	s_addc_u32 s11, s58, s11
	s_add_i32 s9, s40, s1
	s_mov_b32 s15, m0
	s_mov_b32 m0, s9
	s_nop 0
	global_load_lds_dwordx4 v212, s[12:13]
	s_mov_b32 m0, s15
	s_add_i32 s14, s9, 0x2000
	s_mov_b32 s9, m0
	s_mov_b32 m0, s14
	s_nop 0
	global_load_lds_dwordx4 v213, s[10:11]
	s_mov_b32 m0, s9
	s_addk_i32 s1, 0x4000
	s_add_u32 s7, s7, 64
	s_addc_u32 s8, s8, 0
	s_add_i32 s6, s6, 1
	s_mov_b32 s34, 0x8000
	v_add_u32_e32 v100, s34, v191
	v_add3_u32 v135, s34, v203, v198
	v_add_u32_e32 v102, v100, v193
	v_add_u32_e32 v100, v100, v192
	ds_read_b128 v[160:163], v100
	ds_read_b128 v[164:167], v102
	ds_read_b128 v[168:171], v100 offset:2048
	ds_read_b128 v[172:175], v102 offset:2048
	ds_read_b128 v[104:107], v100 offset:4096
	ds_read_b128 v[108:111], v102 offset:4096
	ds_read_b128 v[112:115], v100 offset:6144
	ds_read_b128 v[116:119], v102 offset:6144
	v_add_u32_e32 v103, v135, v199
	v_add_u32_e32 v133, v135, v200
	v_add_u32_e32 v134, v135, v201
	v_add_u32_e32 v135, v135, v202
	s_waitcnt lgkmcnt(4)
; #define LAS __attribute__((address_space(3)))
; __device__ __forceinline__ s16x4 vtr(const LAS unsigned char* p) { return __builtin_bit_cast(s16x4, __builtin_amdgcn_ds_read_tr16_b64_v4i16((LAS v4i16_t*)p)); }
; __device__ __forceinline__ bf16x8 cat8(s16x4 a, s16x4 b) { return (bf16x8){a[0], a[1], a[2], a[3], b[0], b[1], b[2], b[3]}; }
; __device__ __forceinline__ bf16x8 pack8(const f32x4& a, const f32x4& b) { u32x4 w; w.x = pkbf(a[0], a[1]); w.y = pkbf(a[2], a[3]); w.z = pkbf(b[0], b[1]); w.w = pkbf(b[2], b[3]); return __builtin_bit_cast(bf16x8, w); }
;     ...
;     for (int gh = 0; gh < 4 / GPB; ++gh) {
;         f32x4 S[GPB][4];
; #pragma unroll
;         for (int kb = 0; kb < 4; ++kb) {
;             const bf16x8 kf0 = *(const LAS bf16x8*)(kb0 + (16 * kb) * 128 + kx0), kf1 = *(const LAS bf16x8*)(kb0 + (16 * kb) * 128 + kx1);
; #pragma unroll
;             for (int gi = 0; gi < GPB; ++gi) { S[gi][kb] = __builtin_amdgcn_mfma_f32_16x16x32_bf16(kf0, qf[GPB * gh + gi][0], cinit, 0, 0, 0);
;                 S[gi][kb] = __builtin_amdgcn_mfma_f32_16x16x32_bf16(kf1, qf[GPB * gh + gi][1], S[gi][kb], 0, 0, 0); } }
;         bf16x8 pf[GPB][2];
; #pragma unroll
;         for (int gi = 0; gi < GPB; ++gi) {
;             if (MASK) {
; #pragma unroll
;                 for (int kb = 0; kb < 4; ++kb)
; #pragma unroll
;                     for (int i = 0; i < 4; ++i) { const int rel = rel0 + 16 * kb + 4 * g + i; S[gi][kb][i] = ((unsigned)(rel + 128) > 256u) ? NEGBIG : S[gi][kb][i]; }
;             }
;             ls[GPB * gh + gi] += exp_step<4>(S[gi]);
;             pf[gi][0] = pack8(S[gi][0], S[gi][1]); pf[gi][1] = pack8(S[gi][2], S[gi][3]);
;         }
; #pragma unroll
;         for (int kc = 0; kc < 2; ++kc)
; #pragma unroll
;             for (int db = 0; db < 4; ++db) {
;                 const LAS unsigned char* va = vrow + ((db ^ swz) << 5) + (32 * kc) * 128;
;                 const bf16x8 vf = cat8(vtr(va), vtr(va + 16 * 128));
; #pragma unroll
;                 for (int gi = 0; gi < GPB; ++gi) O[GPB * gh + gi][db] = __builtin_amdgcn_mfma_f32_16x16x32_bf16(vf, pf[gi][kc], O[GPB * gh + gi][db], 0, 0, 0);
;             }
;         if (SB == 1) __builtin_amdgcn_sched_barrier(0); else if (SB == 2) __builtin_amdgcn_sched_barrier(0x108);
	v_mfma_f32_16x16x32_bf16 v[136:139], v[160:163], v[4:7], v[0:3]
	v_mfma_f32_16x16x32_bf16 v[140:143], v[168:171], v[4:7], v[0:3]
	v_mfma_f32_16x16x32_bf16 v[136:139], v[164:167], v[12:15], v[136:139]
	v_mfma_f32_16x16x32_bf16 v[140:143], v[172:175], v[12:15], v[140:143]
	ds_read_b64_tr_b16 v[216:217], v103 offset:8192
	ds_read_b64_tr_b16 v[218:219], v103 offset:10240
	ds_read_b64_tr_b16 v[220:221], v133 offset:8192
	ds_read_b64_tr_b16 v[222:223], v133 offset:10240
	ds_read_b64_tr_b16 v[224:225], v134 offset:8192
	ds_read_b64_tr_b16 v[226:227], v134 offset:10240
	ds_read_b64_tr_b16 v[228:229], v135 offset:8192
	ds_read_b64_tr_b16 v[230:231], v135 offset:10240
	v_mfma_f32_16x16x32_bf16 v[176:179], v[160:163], v[8:11], v[0:3]
	v_exp_f32_e32 v136, v136
	v_exp_f32_e32 v137, v137
	v_exp_f32_e32 v138, v138
	v_add_f32_e32 v144, v136, v137
	v_mfma_f32_16x16x32_bf16 v[232:235], v[168:171], v[8:11], v[0:3]
	v_exp_f32_e32 v139, v139
	v_add_f32_e32 v144, v144, v138
	v_exp_f32_e32 v140, v140
	v_add_f32_e32 v144, v144, v139
	v_mfma_f32_16x16x32_bf16 v[176:179], v[164:167], v[16:19], v[176:179]
	v_exp_f32_e32 v141, v141
	v_add_f32_e32 v144, v144, v140
	v_exp_f32_e32 v142, v142
	v_add_f32_e32 v144, v144, v141
	v_cvt_pk_bf16_f32 v136, v136, v137
	v_mfma_f32_16x16x32_bf16 v[232:235], v[172:175], v[16:19], v[232:235]
	v_exp_f32_e32 v143, v143
	v_add_f32_e32 v144, v144, v142
	v_cvt_pk_bf16_f32 v137, v138, v139
	v_cvt_pk_bf16_f32 v138, v140, v141
	v_cvt_pk_bf16_f32 v139, v142, v143
	v_add_f32_e32 v144, v144, v143
	v_add_f32_e32 v131, v131, v144
	s_waitcnt lgkmcnt(0)
	v_mfma_f32_16x16x32_bf16 v[244:247], v[160:163], v[20:23], v[0:3]
	v_exp_f32_e32 v176, v176
	v_exp_f32_e32 v177, v177
	v_mfma_f32_16x16x32_bf16 v[248:251], v[168:171], v[20:23], v[0:3]
	v_exp_f32_e32 v178, v178
	v_add_f32_e32 v144, v176, v177
	v_mfma_f32_16x16x32_bf16 v[244:247], v[164:167], v[24:27], v[244:247]
	v_exp_f32_e32 v179, v179
	v_add_f32_e32 v144, v144, v178
	v_mfma_f32_16x16x32_bf16 v[248:251], v[172:175], v[24:27], v[248:251]
	v_exp_f32_e32 v232, v232
	v_add_f32_e32 v144, v144, v179
	v_mfma_f32_16x16x32_bf16 v[64:67], v[216:219], v[136:139], v[64:67]
	v_exp_f32_e32 v233, v233
	v_add_f32_e32 v144, v144, v232
	v_mfma_f32_16x16x32_bf16 v[60:63], v[220:223], v[136:139], v[60:63]
	v_exp_f32_e32 v234, v234
	v_add_f32_e32 v144, v144, v233
	v_cvt_pk_bf16_f32 v176, v176, v177
	v_mfma_f32_16x16x32_bf16 v[56:59], v[224:227], v[136:139], v[56:59]
	v_exp_f32_e32 v235, v235
	v_add_f32_e32 v144, v144, v234
	v_cvt_pk_bf16_f32 v177, v178, v179
	v_mfma_f32_16x16x32_bf16 v[52:55], v[228:231], v[136:139], v[52:55]
	v_cvt_pk_bf16_f32 v178, v232, v233
	v_cvt_pk_bf16_f32 v179, v234, v235
	v_add_f32_e32 v144, v144, v235
	v_add_f32_e32 v130, v130, v144
	v_mfma_f32_16x16x32_bf16 v[136:139], v[160:163], v[28:31], v[0:3]
	v_exp_f32_e32 v244, v244
	v_exp_f32_e32 v245, v245
	v_mfma_f32_16x16x32_bf16 v[140:143], v[168:171], v[28:31], v[0:3]
	v_exp_f32_e32 v246, v246
	v_add_f32_e32 v144, v244, v245
	v_mfma_f32_16x16x32_bf16 v[136:139], v[164:167], v[32:35], v[136:139]
	v_exp_f32_e32 v247, v247
	v_add_f32_e32 v144, v144, v246
	v_mfma_f32_16x16x32_bf16 v[140:143], v[172:175], v[32:35], v[140:143]
	v_exp_f32_e32 v248, v248
	v_add_f32_e32 v144, v144, v247
	v_mfma_f32_16x16x32_bf16 v[48:51], v[216:219], v[176:179], v[48:51]
	v_exp_f32_e32 v249, v249
	v_add_f32_e32 v144, v144, v248
	v_mfma_f32_16x16x32_bf16 v[44:47], v[220:223], v[176:179], v[44:47]
	v_exp_f32_e32 v250, v250
	v_add_f32_e32 v144, v144, v249
	v_cvt_pk_bf16_f32 v244, v244, v245
	v_mfma_f32_16x16x32_bf16 v[40:43], v[224:227], v[176:179], v[40:43]
	v_exp_f32_e32 v251, v251
	v_add_f32_e32 v144, v144, v250
	v_cvt_pk_bf16_f32 v245, v246, v247
	v_mfma_f32_16x16x32_bf16 v[36:39], v[228:231], v[176:179], v[36:39]
	v_cvt_pk_bf16_f32 v246, v248, v249
	v_cvt_pk_bf16_f32 v247, v250, v251
	v_add_f32_e32 v144, v144, v251
	v_add_f32_e32 v129, v129, v144
	ds_read_b64_tr_b16 v[160:161], v103 offset:12288
	ds_read_b64_tr_b16 v[162:163], v103 offset:14336
	ds_read_b64_tr_b16 v[164:165], v133 offset:12288
	ds_read_b64_tr_b16 v[166:167], v133 offset:14336
	ds_read_b64_tr_b16 v[168:169], v134 offset:12288
	ds_read_b64_tr_b16 v[170:171], v134 offset:14336
	ds_read_b64_tr_b16 v[172:173], v135 offset:12288
	ds_read_b64_tr_b16 v[174:175], v135 offset:14336
	v_mfma_f32_16x16x32_bf16 v[176:179], v[104:107], v[4:7], v[0:3]
	v_exp_f32_e32 v136, v136
	v_exp_f32_e32 v137, v137
	v_mfma_f32_16x16x32_bf16 v[232:235], v[112:115], v[4:7], v[0:3]
	v_exp_f32_e32 v138, v138
	v_add_f32_e32 v144, v136, v137
	v_mfma_f32_16x16x32_bf16 v[176:179], v[108:111], v[12:15], v[176:179]
	v_exp_f32_e32 v139, v139
	v_add_f32_e32 v144, v144, v138
	v_mfma_f32_16x16x32_bf16 v[232:235], v[116:119], v[12:15], v[232:235]
	v_exp_f32_e32 v140, v140
	v_add_f32_e32 v144, v144, v139
	v_mfma_f32_16x16x32_bf16 v[72:75], v[216:219], v[244:247], v[72:75]
	v_exp_f32_e32 v141, v141
	v_add_f32_e32 v144, v144, v140
	v_mfma_f32_16x16x32_bf16 v[84:87], v[220:223], v[244:247], v[84:87]
	v_exp_f32_e32 v142, v142
	v_add_f32_e32 v144, v144, v141
	v_cvt_pk_bf16_f32 v136, v136, v137
	v_mfma_f32_16x16x32_bf16 v[88:91], v[224:227], v[244:247], v[88:91]
	v_exp_f32_e32 v143, v143
	v_add_f32_e32 v144, v144, v142
	v_cvt_pk_bf16_f32 v137, v138, v139
	v_mfma_f32_16x16x32_bf16 v[96:99], v[228:231], v[244:247], v[96:99]
	v_cvt_pk_bf16_f32 v138, v140, v141
	v_cvt_pk_bf16_f32 v139, v142, v143
	v_add_f32_e32 v144, v144, v143
	v_add_f32_e32 v128, v128, v144
	v_mfma_f32_16x16x32_bf16 v[244:247], v[104:107], v[8:11], v[0:3]
	v_exp_f32_e32 v176, v176
	v_exp_f32_e32 v177, v177
	v_mfma_f32_16x16x32_bf16 v[248:251], v[112:115], v[8:11], v[0:3]
	v_exp_f32_e32 v178, v178
	v_add_f32_e32 v144, v176, v177
	v_mfma_f32_16x16x32_bf16 v[244:247], v[108:111], v[16:19], v[244:247]
	v_exp_f32_e32 v179, v179
	v_add_f32_e32 v144, v144, v178
	v_mfma_f32_16x16x32_bf16 v[248:251], v[116:119], v[16:19], v[248:251]
	v_exp_f32_e32 v232, v232
	v_add_f32_e32 v144, v144, v179
	v_mfma_f32_16x16x32_bf16 v[68:71], v[216:219], v[136:139], v[68:71]
	v_exp_f32_e32 v233, v233
	v_add_f32_e32 v144, v144, v232
	v_mfma_f32_16x16x32_bf16 v[76:79], v[220:223], v[136:139], v[76:79]
	v_exp_f32_e32 v234, v234
	v_add_f32_e32 v144, v144, v233
	v_cvt_pk_bf16_f32 v176, v176, v177
	v_mfma_f32_16x16x32_bf16 v[80:83], v[224:227], v[136:139], v[80:83]
	v_exp_f32_e32 v235, v235
	v_add_f32_e32 v144, v144, v234
	v_cvt_pk_bf16_f32 v177, v178, v179
	v_mfma_f32_16x16x32_bf16 v[92:95], v[228:231], v[136:139], v[92:95]
	v_cvt_pk_bf16_f32 v178, v232, v233
	v_cvt_pk_bf16_f32 v179, v234, v235
	v_add_f32_e32 v144, v144, v235
	v_add_f32_e32 v131, v131, v144
	s_waitcnt lgkmcnt(0)
; #define LAS __attribute__((address_space(3)))
; __device__ __forceinline__ s16x4 vtr(const LAS unsigned char* p) { return __builtin_bit_cast(s16x4, __builtin_amdgcn_ds_read_tr16_b64_v4i16((LAS v4i16_t*)p)); }
;     ...
;     for (int gh = 0; gh < 4 / GPB; ++gh) {
;         f32x4 S[GPB][4];
; #pragma unroll
;         for (int kb = 0; kb < 4; ++kb) {
;             const bf16x8 kf0 = *(const LAS bf16x8*)(kb0 + (16 * kb) * 128 + kx0), kf1 = *(const LAS bf16x8*)(kb0 + (16 * kb) * 128 + kx1);
; #pragma unroll
;             for (int gi = 0; gi < GPB; ++gi) { S[gi][kb] = __builtin_amdgcn_mfma_f32_16x16x32_bf16(kf0, qf[GPB * gh + gi][0], cinit, 0, 0, 0);
;                 S[gi][kb] = __builtin_amdgcn_mfma_f32_16x16x32_bf16(kf1, qf[GPB * gh + gi][1], S[gi][kb], 0, 0, 0); } }
;         bf16x8 pf[GPB][2];
; #pragma unroll
;         for (int gi = 0; gi < GPB; ++gi) {
;             if (MASK) {
; #pragma unroll
;                 for (int kb = 0; kb < 4; ++kb)
; #pragma unroll
;                     for (int i = 0; i < 4; ++i) { const int rel = rel0 + 16 * kb + 4 * g + i; S[gi][kb][i] = ((unsigned)(rel + 128) > 256u) ? NEGBIG : S[gi][kb][i]; }
;             }
;             ls[GPB * gh + gi] += exp_step<4>(S[gi]);
;             pf[gi][0] = pack8(S[gi][0], S[gi][1]); pf[gi][1] = pack8(S[gi][2], S[gi][3]);
;         }
; #pragma unroll
;         for (int kc = 0; kc < 2; ++kc)
; #pragma unroll
;             for (int db = 0; db < 4; ++db) {
;                 const LAS unsigned char* va = vrow + ((db ^ swz) << 5) + (32 * kc) * 128;
;                 const bf16x8 vf = cat8(vtr(va), vtr(va + 16 * 128));
; #pragma unroll
;                 for (int gi = 0; gi < GPB; ++gi) O[GPB * gh + gi][db] = __builtin_amdgcn_mfma_f32_16x16x32_bf16(vf, pf[gi][kc], O[GPB * gh + gi][db], 0, 0, 0);
;             }
; __device__ __forceinline__ void swa_phase(LAS unsigned char* lds, const bf16_t* Q, const bf16_t* K, const bf16_t* V, bf16_t* Ob, const float* sink, float negb) {
;     ...
;         for (int t = 0; t < 4; ++t) {
;             dma_tile<1>(lds + ((t + 3) & 3) * SW_BUF, K, V, SW_ROW0(t + 3), 256, dl, w);
;             const LAS unsigned char* buf = lds + (t & 3) * SW_BUF;
;             full_tile<0, 2, 2>(O, ls, qf, negb, buf, buf + 8192, lane, 0);
;             ring_wait<2>();
;         }
	v_mfma_f32_16x16x32_bf16 v[136:139], v[104:107], v[20:23], v[0:3]
	v_exp_f32_e32 v244, v244
	v_exp_f32_e32 v245, v245
	v_mfma_f32_16x16x32_bf16 v[140:143], v[112:115], v[20:23], v[0:3]
	v_exp_f32_e32 v246, v246
	v_add_f32_e32 v144, v244, v245
	v_mfma_f32_16x16x32_bf16 v[136:139], v[108:111], v[24:27], v[136:139]
	v_exp_f32_e32 v247, v247
	v_add_f32_e32 v144, v144, v246
	v_mfma_f32_16x16x32_bf16 v[140:143], v[116:119], v[24:27], v[140:143]
	v_exp_f32_e32 v248, v248
	v_add_f32_e32 v144, v144, v247
	v_mfma_f32_16x16x32_bf16 v[64:67], v[160:163], v[176:179], v[64:67]
	v_exp_f32_e32 v249, v249
	v_add_f32_e32 v144, v144, v248
	v_mfma_f32_16x16x32_bf16 v[60:63], v[164:167], v[176:179], v[60:63]
	v_exp_f32_e32 v250, v250
	v_add_f32_e32 v144, v144, v249
	v_cvt_pk_bf16_f32 v244, v244, v245
	v_mfma_f32_16x16x32_bf16 v[56:59], v[168:171], v[176:179], v[56:59]
	v_exp_f32_e32 v251, v251
	v_add_f32_e32 v144, v144, v250
	v_cvt_pk_bf16_f32 v245, v246, v247
	v_mfma_f32_16x16x32_bf16 v[52:55], v[172:175], v[176:179], v[52:55]
	v_cvt_pk_bf16_f32 v246, v248, v249
	v_cvt_pk_bf16_f32 v247, v250, v251
	v_add_f32_e32 v144, v144, v251
	v_add_f32_e32 v130, v130, v144
	v_mfma_f32_16x16x32_bf16 v[176:179], v[104:107], v[28:31], v[0:3]
	v_exp_f32_e32 v136, v136
	v_exp_f32_e32 v137, v137
	v_mfma_f32_16x16x32_bf16 v[232:235], v[112:115], v[28:31], v[0:3]
	v_exp_f32_e32 v138, v138
	v_add_f32_e32 v144, v136, v137
	v_mfma_f32_16x16x32_bf16 v[176:179], v[108:111], v[32:35], v[176:179]
	v_exp_f32_e32 v139, v139
	v_add_f32_e32 v144, v144, v138
	v_mfma_f32_16x16x32_bf16 v[232:235], v[116:119], v[32:35], v[232:235]
	v_exp_f32_e32 v140, v140
	v_add_f32_e32 v144, v144, v139
	v_mfma_f32_16x16x32_bf16 v[48:51], v[160:163], v[244:247], v[48:51]
	v_exp_f32_e32 v141, v141
	v_add_f32_e32 v144, v144, v140
	v_mfma_f32_16x16x32_bf16 v[44:47], v[164:167], v[244:247], v[44:47]
	v_exp_f32_e32 v142, v142
	v_add_f32_e32 v144, v144, v141
	v_cvt_pk_bf16_f32 v136, v136, v137
	v_mfma_f32_16x16x32_bf16 v[40:43], v[168:171], v[244:247], v[40:43]
	v_exp_f32_e32 v143, v143
	v_add_f32_e32 v144, v144, v142
	v_cvt_pk_bf16_f32 v137, v138, v139
	v_mfma_f32_16x16x32_bf16 v[36:39], v[172:175], v[244:247], v[36:39]
	v_cvt_pk_bf16_f32 v138, v140, v141
	v_cvt_pk_bf16_f32 v139, v142, v143
	v_add_f32_e32 v144, v144, v143
	v_add_f32_e32 v129, v129, v144
	v_mfma_f32_16x16x32_bf16 v[72:75], v[160:163], v[136:139], v[72:75]
	v_exp_f32_e32 v176, v176
	v_exp_f32_e32 v177, v177
	v_exp_f32_e32 v178, v178
	v_add_f32_e32 v144, v176, v177
	v_mfma_f32_16x16x32_bf16 v[84:87], v[164:167], v[136:139], v[84:87]
	v_exp_f32_e32 v179, v179
	v_add_f32_e32 v144, v144, v178
	v_exp_f32_e32 v232, v232
	v_add_f32_e32 v144, v144, v179
	v_mfma_f32_16x16x32_bf16 v[88:91], v[168:171], v[136:139], v[88:91]
	v_exp_f32_e32 v233, v233
	v_add_f32_e32 v144, v144, v232
	v_exp_f32_e32 v234, v234
	v_add_f32_e32 v144, v144, v233
	v_cvt_pk_bf16_f32 v176, v176, v177
	v_mfma_f32_16x16x32_bf16 v[96:99], v[172:175], v[136:139], v[96:99]
	v_exp_f32_e32 v235, v235
	v_add_f32_e32 v144, v144, v234
	v_cvt_pk_bf16_f32 v177, v178, v179
	v_cvt_pk_bf16_f32 v178, v232, v233
	v_cvt_pk_bf16_f32 v179, v234, v235
	v_add_f32_e32 v144, v144, v235
	v_add_f32_e32 v128, v128, v144
	v_mfma_f32_16x16x32_bf16 v[68:71], v[160:163], v[176:179], v[68:71]
	v_mfma_f32_16x16x32_bf16 v[76:79], v[164:167], v[176:179], v[76:79]
	v_mfma_f32_16x16x32_bf16 v[80:83], v[168:171], v[176:179], v[80:83]
	v_mfma_f32_16x16x32_bf16 v[92:95], v[172:175], v[176:179], v[92:95]
	s_mov_b32 s34, 0xc000
	v_add_u32_e32 v100, s34, v191
	v_add3_u32 v135, s34, v203, v198
	v_add_u32_e32 v102, v100, v193
	v_add_u32_e32 v100, v100, v192
	ds_read_b128 v[160:163], v100
	ds_read_b128 v[164:167], v102
	ds_read_b128 v[168:171], v100 offset:2048
	ds_read_b128 v[172:175], v102 offset:2048
	ds_read_b128 v[104:107], v100 offset:4096
	ds_read_b128 v[108:111], v102 offset:4096
	ds_read_b128 v[112:115], v100 offset:6144
	ds_read_b128 v[116:119], v102 offset:6144
	v_add_u32_e32 v103, v135, v199
	v_add_u32_e32 v133, v135, v200
	v_add_u32_e32 v134, v135, v201
	v_add_u32_e32 v135, v135, v202
	s_waitcnt lgkmcnt(4)
	v_mfma_f32_16x16x32_bf16 v[136:139], v[160:163], v[4:7], v[0:3]
	v_mfma_f32_16x16x32_bf16 v[140:143], v[168:171], v[4:7], v[0:3]
	v_mfma_f32_16x16x32_bf16 v[136:139], v[164:167], v[12:15], v[136:139]
	v_mfma_f32_16x16x32_bf16 v[140:143], v[172:175], v[12:15], v[140:143]
	ds_read_b64_tr_b16 v[216:217], v103 offset:8192
	ds_read_b64_tr_b16 v[218:219], v103 offset:10240
	ds_read_b64_tr_b16 v[220:221], v133 offset:8192
	ds_read_b64_tr_b16 v[222:223], v133 offset:10240
	ds_read_b64_tr_b16 v[224:225], v134 offset:8192
	ds_read_b64_tr_b16 v[226:227], v134 offset:10240
	ds_read_b64_tr_b16 v[228:229], v135 offset:8192
	ds_read_b64_tr_b16 v[230:231], v135 offset:10240
	v_mfma_f32_16x16x32_bf16 v[176:179], v[160:163], v[8:11], v[0:3]
	v_exp_f32_e32 v136, v136
	v_exp_f32_e32 v137, v137
	v_exp_f32_e32 v138, v138
	v_add_f32_e32 v144, v136, v137
	v_mfma_f32_16x16x32_bf16 v[232:235], v[168:171], v[8:11], v[0:3]
	v_exp_f32_e32 v139, v139
	v_add_f32_e32 v144, v144, v138
	v_exp_f32_e32 v140, v140
	v_add_f32_e32 v144, v144, v139
	v_mfma_f32_16x16x32_bf16 v[176:179], v[164:167], v[16:19], v[176:179]
	v_exp_f32_e32 v141, v141
	v_add_f32_e32 v144, v144, v140
	v_exp_f32_e32 v142, v142
	v_add_f32_e32 v144, v144, v141
	v_cvt_pk_bf16_f32 v136, v136, v137
	v_mfma_f32_16x16x32_bf16 v[232:235], v[172:175], v[16:19], v[232:235]
	v_exp_f32_e32 v143, v143
	v_add_f32_e32 v144, v144, v142
	v_cvt_pk_bf16_f32 v137, v138, v139
	v_cvt_pk_bf16_f32 v138, v140, v141
	v_cvt_pk_bf16_f32 v139, v142, v143
	v_add_f32_e32 v144, v144, v143
	v_add_f32_e32 v131, v131, v144
	s_waitcnt lgkmcnt(0)
; #define LAS __attribute__((address_space(3)))
; __device__ __forceinline__ s16x4 vtr(const LAS unsigned char* p) { return __builtin_bit_cast(s16x4, __builtin_amdgcn_ds_read_tr16_b64_v4i16((LAS v4i16_t*)p)); }
; __device__ __forceinline__ bf16x8 cat8(s16x4 a, s16x4 b) { return (bf16x8){a[0], a[1], a[2], a[3], b[0], b[1], b[2], b[3]}; }
; __device__ __forceinline__ bf16x8 pack8(const f32x4& a, const f32x4& b) { u32x4 w; w.x = pkbf(a[0], a[1]); w.y = pkbf(a[2], a[3]); w.z = pkbf(b[0], b[1]); w.w = pkbf(b[2], b[3]); return __builtin_bit_cast(bf16x8, w); }
;     ...
;     for (int gh = 0; gh < 4 / GPB; ++gh) {
;         f32x4 S[GPB][4];
; #pragma unroll
;         for (int kb = 0; kb < 4; ++kb) {
;             const bf16x8 kf0 = *(const LAS bf16x8*)(kb0 + (16 * kb) * 128 + kx0), kf1 = *(const LAS bf16x8*)(kb0 + (16 * kb) * 128 + kx1);
; #pragma unroll
;             for (int gi = 0; gi < GPB; ++gi) { S[gi][kb] = __builtin_amdgcn_mfma_f32_16x16x32_bf16(kf0, qf[GPB * gh + gi][0], cinit, 0, 0, 0);
;                 S[gi][kb] = __builtin_amdgcn_mfma_f32_16x16x32_bf16(kf1, qf[GPB * gh + gi][1], S[gi][kb], 0, 0, 0); } }
;         bf16x8 pf[GPB][2];
; #pragma unroll
;         for (int gi = 0; gi < GPB; ++gi) {
;             if (MASK) {
; #pragma unroll
;                 for (int kb = 0; kb < 4; ++kb)
; #pragma unroll
;                     for (int i = 0; i < 4; ++i) { const int rel = rel0 + 16 * kb + 4 * g + i; S[gi][kb][i] = ((unsigned)(rel + 128) > 256u) ? NEGBIG : S[gi][kb][i]; }
;             }
;             ls[GPB * gh + gi] += exp_step<4>(S[gi]);
;             pf[gi][0] = pack8(S[gi][0], S[gi][1]); pf[gi][1] = pack8(S[gi][2], S[gi][3]);
;         }
; #pragma unroll
;         for (int kc = 0; kc < 2; ++kc)
; #pragma unroll
;             for (int db = 0; db < 4; ++db) {
;                 const LAS unsigned char* va = vrow + ((db ^ swz) << 5) + (32 * kc) * 128;
;                 const bf16x8 vf = cat8(vtr(va), vtr(va + 16 * 128));
; #pragma unroll
;                 for (int gi = 0; gi < GPB; ++gi) O[GPB * gh + gi][db] = __builtin_amdgcn_mfma_f32_16x16x32_bf16(vf, pf[gi][kc], O[GPB * gh + gi][db], 0, 0, 0);
;             }
	v_mfma_f32_16x16x32_bf16 v[244:247], v[160:163], v[20:23], v[0:3]
	v_exp_f32_e32 v176, v176
	v_exp_f32_e32 v177, v177
	v_mfma_f32_16x16x32_bf16 v[248:251], v[168:171], v[20:23], v[0:3]
	v_exp_f32_e32 v178, v178
	v_add_f32_e32 v144, v176, v177
	v_mfma_f32_16x16x32_bf16 v[244:247], v[164:167], v[24:27], v[244:247]
	v_exp_f32_e32 v179, v179
	v_add_f32_e32 v144, v144, v178
	v_mfma_f32_16x16x32_bf16 v[248:251], v[172:175], v[24:27], v[248:251]
	v_exp_f32_e32 v232, v232
	v_add_f32_e32 v144, v144, v179
	v_mfma_f32_16x16x32_bf16 v[64:67], v[216:219], v[136:139], v[64:67]
	v_exp_f32_e32 v233, v233
	v_add_f32_e32 v144, v144, v232
	v_mfma_f32_16x16x32_bf16 v[60:63], v[220:223], v[136:139], v[60:63]
	v_exp_f32_e32 v234, v234
	v_add_f32_e32 v144, v144, v233
	v_cvt_pk_bf16_f32 v176, v176, v177
	v_mfma_f32_16x16x32_bf16 v[56:59], v[224:227], v[136:139], v[56:59]
	v_exp_f32_e32 v235, v235
	v_add_f32_e32 v144, v144, v234
	v_cvt_pk_bf16_f32 v177, v178, v179
	v_mfma_f32_16x16x32_bf16 v[52:55], v[228:231], v[136:139], v[52:55]
	v_cvt_pk_bf16_f32 v178, v232, v233
	v_cvt_pk_bf16_f32 v179, v234, v235
	v_add_f32_e32 v144, v144, v235
	v_add_f32_e32 v130, v130, v144
	v_mfma_f32_16x16x32_bf16 v[136:139], v[160:163], v[28:31], v[0:3]
	v_exp_f32_e32 v244, v244
	v_exp_f32_e32 v245, v245
	v_mfma_f32_16x16x32_bf16 v[140:143], v[168:171], v[28:31], v[0:3]
	v_exp_f32_e32 v246, v246
	v_add_f32_e32 v144, v244, v245
	v_mfma_f32_16x16x32_bf16 v[136:139], v[164:167], v[32:35], v[136:139]
	v_exp_f32_e32 v247, v247
	v_add_f32_e32 v144, v144, v246
	v_mfma_f32_16x16x32_bf16 v[140:143], v[172:175], v[32:35], v[140:143]
	v_exp_f32_e32 v248, v248
	v_add_f32_e32 v144, v144, v247
	v_mfma_f32_16x16x32_bf16 v[48:51], v[216:219], v[176:179], v[48:51]
	v_exp_f32_e32 v249, v249
	v_add_f32_e32 v144, v144, v248
	v_mfma_f32_16x16x32_bf16 v[44:47], v[220:223], v[176:179], v[44:47]
	v_exp_f32_e32 v250, v250
	v_add_f32_e32 v144, v144, v249
	v_cvt_pk_bf16_f32 v244, v244, v245
	v_mfma_f32_16x16x32_bf16 v[40:43], v[224:227], v[176:179], v[40:43]
	v_exp_f32_e32 v251, v251
	v_add_f32_e32 v144, v144, v250
	v_cvt_pk_bf16_f32 v245, v246, v247
	v_mfma_f32_16x16x32_bf16 v[36:39], v[228:231], v[176:179], v[36:39]
	v_cvt_pk_bf16_f32 v246, v248, v249
	v_cvt_pk_bf16_f32 v247, v250, v251
	v_add_f32_e32 v144, v144, v251
	v_add_f32_e32 v129, v129, v144
	ds_read_b64_tr_b16 v[160:161], v103 offset:12288
	ds_read_b64_tr_b16 v[162:163], v103 offset:14336
	ds_read_b64_tr_b16 v[164:165], v133 offset:12288
	ds_read_b64_tr_b16 v[166:167], v133 offset:14336
	ds_read_b64_tr_b16 v[168:169], v134 offset:12288
	ds_read_b64_tr_b16 v[170:171], v134 offset:14336
	ds_read_b64_tr_b16 v[172:173], v135 offset:12288
	ds_read_b64_tr_b16 v[174:175], v135 offset:14336
	v_mfma_f32_16x16x32_bf16 v[176:179], v[104:107], v[4:7], v[0:3]
	v_exp_f32_e32 v136, v136
	v_exp_f32_e32 v137, v137
	v_mfma_f32_16x16x32_bf16 v[232:235], v[112:115], v[4:7], v[0:3]
	v_exp_f32_e32 v138, v138
	v_add_f32_e32 v144, v136, v137
	v_mfma_f32_16x16x32_bf16 v[176:179], v[108:111], v[12:15], v[176:179]
	v_exp_f32_e32 v139, v139
	v_add_f32_e32 v144, v144, v138
	v_mfma_f32_16x16x32_bf16 v[232:235], v[116:119], v[12:15], v[232:235]
	v_exp_f32_e32 v140, v140
	v_add_f32_e32 v144, v144, v139
	v_mfma_f32_16x16x32_bf16 v[72:75], v[216:219], v[244:247], v[72:75]
	v_exp_f32_e32 v141, v141
	v_add_f32_e32 v144, v144, v140
	v_mfma_f32_16x16x32_bf16 v[84:87], v[220:223], v[244:247], v[84:87]
	v_exp_f32_e32 v142, v142
	v_add_f32_e32 v144, v144, v141
	v_cvt_pk_bf16_f32 v136, v136, v137
	v_mfma_f32_16x16x32_bf16 v[88:91], v[224:227], v[244:247], v[88:91]
	v_exp_f32_e32 v143, v143
	v_add_f32_e32 v144, v144, v142
	v_cvt_pk_bf16_f32 v137, v138, v139
	v_mfma_f32_16x16x32_bf16 v[96:99], v[228:231], v[244:247], v[96:99]
	v_cvt_pk_bf16_f32 v138, v140, v141
	v_cvt_pk_bf16_f32 v139, v142, v143
	v_add_f32_e32 v144, v144, v143
	v_add_f32_e32 v128, v128, v144
	v_mfma_f32_16x16x32_bf16 v[244:247], v[104:107], v[8:11], v[0:3]
	v_exp_f32_e32 v176, v176
	v_exp_f32_e32 v177, v177
	v_mfma_f32_16x16x32_bf16 v[248:251], v[112:115], v[8:11], v[0:3]
	v_exp_f32_e32 v178, v178
	v_add_f32_e32 v144, v176, v177
	v_mfma_f32_16x16x32_bf16 v[244:247], v[108:111], v[16:19], v[244:247]
	v_exp_f32_e32 v179, v179
	v_add_f32_e32 v144, v144, v178
	v_mfma_f32_16x16x32_bf16 v[248:251], v[116:119], v[16:19], v[248:251]
	v_exp_f32_e32 v232, v232
	v_add_f32_e32 v144, v144, v179
	v_mfma_f32_16x16x32_bf16 v[68:71], v[216:219], v[136:139], v[68:71]
	v_exp_f32_e32 v233, v233
	v_add_f32_e32 v144, v144, v232
	v_mfma_f32_16x16x32_bf16 v[76:79], v[220:223], v[136:139], v[76:79]
	v_exp_f32_e32 v234, v234
	v_add_f32_e32 v144, v144, v233
	v_cvt_pk_bf16_f32 v176, v176, v177
	v_mfma_f32_16x16x32_bf16 v[80:83], v[224:227], v[136:139], v[80:83]
	v_exp_f32_e32 v235, v235
	v_add_f32_e32 v144, v144, v234
	v_cvt_pk_bf16_f32 v177, v178, v179
	v_mfma_f32_16x16x32_bf16 v[92:95], v[228:231], v[136:139], v[92:95]
	v_cvt_pk_bf16_f32 v178, v232, v233
	v_cvt_pk_bf16_f32 v179, v234, v235
	v_add_f32_e32 v144, v144, v235
	v_add_f32_e32 v131, v131, v144
	s_waitcnt lgkmcnt(0)
; #define LAS __attribute__((address_space(3)))
; __device__ __forceinline__ s16x4 vtr(const LAS unsigned char* p) { return __builtin_bit_cast(s16x4, __builtin_amdgcn_ds_read_tr16_b64_v4i16((LAS v4i16_t*)p)); }
; __device__ __forceinline__ bf16x8 cat8(s16x4 a, s16x4 b) { return (bf16x8){a[0], a[1], a[2], a[3], b[0], b[1], b[2], b[3]}; }
; template <int NI> __device__ __forceinline__ void ring_wait() { asm volatile("s_waitcnt vmcnt(%0)" :: "n"(2 * NI) : "memory"); __syncthreads(); }
;     ...
;         for (int kc = 0; kc < 2; ++kc)
; #pragma unroll
;             for (int db = 0; db < 4; ++db) {
;                 const LAS unsigned char* va = vrow + ((db ^ swz) << 5) + (32 * kc) * 128;
;                 const bf16x8 vf = cat8(vtr(va), vtr(va + 16 * 128));
; #pragma unroll
;                 for (int gi = 0; gi < GPB; ++gi) O[GPB * gh + gi][db] = __builtin_amdgcn_mfma_f32_16x16x32_bf16(vf, pf[gi][kc], O[GPB * gh + gi][db], 0, 0, 0);
;             }
; __device__ __forceinline__ void swa_phase(LAS unsigned char* lds, const bf16_t* Q, const bf16_t* K, const bf16_t* V, bf16_t* Ob, const float* sink, float negb) {
;     ...
;         for (int t = 0; t < 4; ++t) {
;             dma_tile<1>(lds + ((t + 3) & 3) * SW_BUF, K, V, SW_ROW0(t + 3), 256, dl, w);
;             const LAS unsigned char* buf = lds + (t & 3) * SW_BUF;
;             full_tile<0, 2, 2>(O, ls, qf, negb, buf, buf + 8192, lane, 0);
;             ring_wait<2>();
;         }
;         for (int t = 4; t < NT; ++t) {
	v_mfma_f32_16x16x32_bf16 v[136:139], v[104:107], v[20:23], v[0:3]
	v_exp_f32_e32 v244, v244
	v_exp_f32_e32 v245, v245
	v_mfma_f32_16x16x32_bf16 v[140:143], v[112:115], v[20:23], v[0:3]
	v_exp_f32_e32 v246, v246
	v_add_f32_e32 v144, v244, v245
	v_mfma_f32_16x16x32_bf16 v[136:139], v[108:111], v[24:27], v[136:139]
	v_exp_f32_e32 v247, v247
	v_add_f32_e32 v144, v144, v246
	v_mfma_f32_16x16x32_bf16 v[140:143], v[116:119], v[24:27], v[140:143]
	v_exp_f32_e32 v248, v248
	v_add_f32_e32 v144, v144, v247
	v_mfma_f32_16x16x32_bf16 v[64:67], v[160:163], v[176:179], v[64:67]
	v_exp_f32_e32 v249, v249
	v_add_f32_e32 v144, v144, v248
	v_mfma_f32_16x16x32_bf16 v[60:63], v[164:167], v[176:179], v[60:63]
	v_exp_f32_e32 v250, v250
	v_add_f32_e32 v144, v144, v249
	v_cvt_pk_bf16_f32 v244, v244, v245
	v_mfma_f32_16x16x32_bf16 v[56:59], v[168:171], v[176:179], v[56:59]
	v_exp_f32_e32 v251, v251
	v_add_f32_e32 v144, v144, v250
	v_cvt_pk_bf16_f32 v245, v246, v247
	v_mfma_f32_16x16x32_bf16 v[52:55], v[172:175], v[176:179], v[52:55]
	v_cvt_pk_bf16_f32 v246, v248, v249
	v_cvt_pk_bf16_f32 v247, v250, v251
	v_add_f32_e32 v144, v144, v251
	v_add_f32_e32 v130, v130, v144
	v_mfma_f32_16x16x32_bf16 v[176:179], v[104:107], v[28:31], v[0:3]
	v_exp_f32_e32 v136, v136
	v_exp_f32_e32 v137, v137
	v_mfma_f32_16x16x32_bf16 v[232:235], v[112:115], v[28:31], v[0:3]
	v_exp_f32_e32 v138, v138
	v_add_f32_e32 v144, v136, v137
	v_mfma_f32_16x16x32_bf16 v[176:179], v[108:111], v[32:35], v[176:179]
	v_exp_f32_e32 v139, v139
	v_add_f32_e32 v144, v144, v138
	v_mfma_f32_16x16x32_bf16 v[232:235], v[116:119], v[32:35], v[232:235]
	v_exp_f32_e32 v140, v140
	v_add_f32_e32 v144, v144, v139
	v_mfma_f32_16x16x32_bf16 v[48:51], v[160:163], v[244:247], v[48:51]
	v_exp_f32_e32 v141, v141
	v_add_f32_e32 v144, v144, v140
	v_mfma_f32_16x16x32_bf16 v[44:47], v[164:167], v[244:247], v[44:47]
	v_exp_f32_e32 v142, v142
	v_add_f32_e32 v144, v144, v141
	v_cvt_pk_bf16_f32 v136, v136, v137
	v_mfma_f32_16x16x32_bf16 v[40:43], v[168:171], v[244:247], v[40:43]
	v_exp_f32_e32 v143, v143
	v_add_f32_e32 v144, v144, v142
	v_cvt_pk_bf16_f32 v137, v138, v139
	v_mfma_f32_16x16x32_bf16 v[36:39], v[172:175], v[244:247], v[36:39]
	v_cvt_pk_bf16_f32 v138, v140, v141
	v_cvt_pk_bf16_f32 v139, v142, v143
	v_add_f32_e32 v144, v144, v143
	v_add_f32_e32 v129, v129, v144
	v_mfma_f32_16x16x32_bf16 v[72:75], v[160:163], v[136:139], v[72:75]
	v_exp_f32_e32 v176, v176
	v_exp_f32_e32 v177, v177
	v_exp_f32_e32 v178, v178
	v_add_f32_e32 v144, v176, v177
	v_mfma_f32_16x16x32_bf16 v[84:87], v[164:167], v[136:139], v[84:87]
	v_exp_f32_e32 v179, v179
	v_add_f32_e32 v144, v144, v178
	v_exp_f32_e32 v232, v232
	v_add_f32_e32 v144, v144, v179
	v_mfma_f32_16x16x32_bf16 v[88:91], v[168:171], v[136:139], v[88:91]
	v_exp_f32_e32 v233, v233
	v_add_f32_e32 v144, v144, v232
	v_exp_f32_e32 v234, v234
	v_add_f32_e32 v144, v144, v233
	v_cvt_pk_bf16_f32 v176, v176, v177
	v_mfma_f32_16x16x32_bf16 v[96:99], v[172:175], v[136:139], v[96:99]
	v_exp_f32_e32 v235, v235
	v_add_f32_e32 v144, v144, v234
	v_cvt_pk_bf16_f32 v177, v178, v179
	v_cvt_pk_bf16_f32 v178, v232, v233
	v_cvt_pk_bf16_f32 v179, v234, v235
	v_add_f32_e32 v144, v144, v235
	v_add_f32_e32 v128, v128, v144
	v_mfma_f32_16x16x32_bf16 v[68:71], v[160:163], v[176:179], v[68:71]
	v_mfma_f32_16x16x32_bf16 v[76:79], v[164:167], v[176:179], v[76:79]
	v_mfma_f32_16x16x32_bf16 v[80:83], v[168:171], v[176:179], v[80:83]
	v_mfma_f32_16x16x32_bf16 v[92:95], v[172:175], v[176:179], v[92:95]
	s_waitcnt vmcnt(2)
	s_barrier
	s_cmp_lt_u32 s6, s46
	s_cselect_b32 s11, s8, 0
	s_cselect_b32 s10, s7, s82
	s_lshl_b64 s[10:11], s[10:11], 9
	s_add_u32 s12, s67, s10
	s_addc_u32 s13, s4, s11
	s_add_u32 s10, s5, s10
	s_addc_u32 s11, s58, s11
	s_add_i32 s9, s40, s1
	s_mov_b32 s15, m0
	s_mov_b32 m0, s9
	s_nop 0
	global_load_lds_dwordx4 v212, s[12:13]
	s_mov_b32 m0, s15
	s_add_i32 s14, s9, 0x2000
	s_mov_b32 s9, m0
	s_mov_b32 m0, s14
	s_nop 0
	global_load_lds_dwordx4 v213, s[10:11]
	s_mov_b32 m0, s9
	s_addk_i32 s1, 0x4000
	s_add_u32 s7, s7, 64
	s_addc_u32 s8, s8, 0
	s_add_i32 s6, s6, 1
	s_add_i32 s48, s0, 0xffffff80
	s_add_i32 s49, s0, 0x8f
	s_add_i32 s50, s45, 0xffffffbf
	s_mov_b32 s51, 0
	s_mov_b32 s52, 0x10000
	v_mov_b32_e32 v132, v211
	s_branch .LBB0_355
